# v15: attention K/V fragment prefetch + GLA G1/G3: stage loads issued together, gate weight/bias loads hoisted
# speedup vs baseline: 1.0259x; 1.0134x over previous
.LBB0_131:
	s_ashr_i32 s0, s10, 9
	s_ashr_i32 s1, s0, 31
	s_lshl_b64 s[30:31], s[0:1], 13
	s_and_b32 s0, s66, 0x1fc0
	s_or_b32 s30, s30, s0
	v_lshl_add_u64 v[0:1], s[30:31], 0, v[90:91]
	v_mov_b64_e32 v[8:9], s[6:7]
	s_movk_i32 s26, 0x1a00
	v_lshl_add_u64 v[10:11], s[30:31], 0, v[92:93]
	s_bfe_u32 s5, s10, 0x20007
	v_mad_u64_u32 v[2:3], s[0:1], v0, s26, v[8:9]
	v_mad_u64_u32 v[8:9], s[0:1], v10, s26, v[8:9]
	v_mad_i32_i24 v3, v1, s26, v3
	s_lshl_b32 s2, s5, 8
	s_mov_b32 s3, s4
	v_mad_i32_i24 v9, v11, s26, v9
	v_lshl_add_u64 v[0:1], v[2:3], 0, s[2:3]
	v_lshl_add_u64 v[8:9], v[8:9], 0, s[2:3]
	v_lshl_add_u64 v[4:5], v[0:1], 0, v[192:193]
	v_lshl_add_u64 v[12:13], v[8:9], 0, v[192:193]
	global_load_dwordx4 v[216:219], v[4:5], off offset:1024
	s_nop 0
	global_load_dwordx4 v[220:223], v[4:5], off
	s_nop 0
	global_load_dwordx4 v[224:227], v[12:13], off offset:1024
	s_nop 0
	global_load_dwordx4 v[228:231], v[12:13], off
	v_add_u32_e32 v16, v141, v143
	s_lshl_b32 s3, s5, 7
	v_add_u32_e32 v17, v142, v143
	v_add_u32_e32 v18, v141, v144
	v_add_u32_e32 v19, v142, v144
	s_mov_b64 s[0:1], exec
	v_readlane_b32 s24, v245, 34
	v_readlane_b32 s25, v245, 35
	s_and_b64 s[24:25], s[0:1], s[24:25]
	s_mov_b64 exec, s[24:25]
	s_cbranch_execz .LBB0_133
	v_lshl_add_u64 v[0:1], s[30:31], 0, v[94:95]
	v_mov_b64_e32 v[2:3], s[6:7]
	v_mad_u64_u32 v[2:3], s[24:25], v0, s26, v[2:3]
	v_mov_b32_e32 v0, v3
	v_mad_u64_u32 v[0:1], s[24:25], v1, s26, v[0:1]
	v_mov_b32_e32 v3, v0
	v_mov_b32_e32 v113, v193
	v_lshl_add_u64 v[0:1], v[2:3], 0, v[112:113]
	v_add_co_u32_e32 v0, vcc, 0x1000, v0
	s_nop 1
	v_addc_co_u32_e32 v1, vcc, 0, v1, vcc
	global_load_dwordx4 v[186:189], v[0:1], off offset:2048
.LBB0_133:
	s_or_b64 exec, exec, s[0:1]
	v_lshl_add_u64 v[2:3], s[30:31], 0, v[96:97]
	v_mov_b64_e32 v[0:1], s[6:7]
	v_mad_u64_u32 v[4:5], s[0:1], v2, s26, v[0:1]
	v_mov_b32_e32 v2, v5
	v_mad_u64_u32 v[2:3], s[0:1], v3, s26, v[2:3]
	v_mov_b32_e32 v5, v2
	s_lshl_b32 s0, s5, 9
	s_mov_b32 s1, s4
	v_lshl_add_u64 v[2:3], v[4:5], 0, s[0:1]
	v_mov_b32_e32 v115, v193
	v_lshl_add_u64 v[2:3], v[2:3], 0, v[114:115]
	global_load_dwordx4 v[232:235], v[2:3], off offset:2048
	s_ashr_i32 s11, s10, 31
	v_or_b32_e32 v138, s30, v88
	s_mul_i32 s5, s31, 0x1a00
	v_or_b32_e32 v128, s30, v108
	v_mov_b32_e32 v117, v193
	s_mov_b64 s[80:81], 0x1000
	v_mov_b32_e32 v139, s31
	v_mov_b32_e32 v129, s31
	v_add_u32_e32 v113, 0xb000, v165
	v_lshl_add_u64 v[2:3], s[30:31], 0, v[98:99]
	v_mad_u64_u32 v[4:5], s[24:25], v2, s26, v[0:1]
	v_mov_b32_e32 v2, v5
	v_mad_u64_u32 v[2:3], s[24:25], v3, s26, v[2:3]
	v_mov_b32_e32 v5, v2
	v_lshl_add_u64 v[2:3], v[4:5], 0, s[0:1]
	v_lshl_add_u64 v[2:3], v[2:3], 0, v[114:115]
	global_load_dwordx4 v[236:239], v[2:3], off offset:2048
	v_lshl_add_u64 v[2:3], s[30:31], 0, v[100:101]
	v_mad_u64_u32 v[4:5], s[24:25], v2, s26, v[0:1]
	v_mov_b32_e32 v2, v5
	v_mad_u64_u32 v[2:3], s[24:25], v3, s26, v[2:3]
	v_mov_b32_e32 v5, v2
	v_lshl_add_u64 v[2:3], v[4:5], 0, s[0:1]
	v_lshl_add_u64 v[2:3], v[2:3], 0, v[114:115]
	global_load_dwordx4 v[240:243], v[2:3], off offset:2048
	v_lshl_add_u64 v[2:3], s[30:31], 0, v[102:103]
	v_mad_u64_u32 v[4:5], s[24:25], v2, s26, v[0:1]
	v_mov_b32_e32 v2, v5
	v_mad_u64_u32 v[2:3], s[24:25], v3, s26, v[2:3]
	v_mov_b32_e32 v5, v2
	v_lshl_add_u64 v[2:3], v[4:5], 0, s[0:1]
	v_lshl_add_u64 v[2:3], v[2:3], 0, v[114:115]
	global_load_dwordx4 v[182:185], v[2:3], off offset:2048
	s_lshl_b64 s[24:25], s[10:11], 16
	s_movk_i32 s11, 0x1000
	s_mov_b64 s[30:31], s[64:65]
	v_add_u32_e32 v115, 0xb000, v166
	s_waitcnt vmcnt(0)
	ds_write_b128 v16, v[216:219]
	ds_write_b128 v17, v[220:223]
	ds_write_b128 v18, v[224:227]
	ds_write_b128 v19, v[228:231]
	ds_write_b128 v151, v[232:235] offset:8192
	ds_write_b128 v152, v[236:239] offset:8192
	ds_write_b128 v153, v[240:243] offset:8192
	ds_write_b128 v154, v[182:185] offset:8192
	v_cmp_gt_u32_e32 vcc, 0x80, v195
	s_and_saveexec_b64 s[100:101], vcc
	ds_write_b128 v150, v[186:189]
	s_or_b64 exec, exec, s[100:101]
	v_readfirstlane_b32 s100, v89
	s_lshr_b32 s100, s100, 1
	s_and_b32 s100, s100, 0x60
	v_or_b32_e32 v222, s3, v88
	v_or_b32_e32 v222, s100, v222
	v_lshlrev_b32_e32 v220, 5, v222
	v_mov_b32_e32 v221, v193
	v_lshl_add_u64 v[220:221], v[106:107], 0, v[220:221]
	global_load_dwordx4 v[216:219], v[220:221], off
	v_readlane_b32 s100, v245, 38
	v_readlane_b32 s101, v245, 39
	v_lshlrev_b32_e32 v222, 2, v222
	s_nop 4
	global_load_dword v223, v222, s[100:101]
	v_lshl_add_u64 v[2:3], v[104:105], 0, s[24:25]
	v_readlane_b32 s24, v245, 58
	v_readlane_b32 s25, v245, 59
	s_nop 1
	v_lshl_add_u64 v[4:5], v[2:3], 0, s[24:25]
	v_readlane_b32 s24, v245, 46
	v_readlane_b32 s25, v245, 47
	global_load_dwordx4 v[60:63], v[4:5], off
	s_nop 0
	v_lshl_add_u64 v[4:5], v[2:3], 0, s[24:25]
	v_readlane_b32 s24, v245, 48
	v_readlane_b32 s25, v245, 49
	global_load_dwordx4 v[56:59], v[4:5], off
	s_nop 0
	v_lshl_add_u64 v[4:5], v[2:3], 0, s[24:25]
	v_readlane_b32 s24, v245, 50
	v_readlane_b32 s25, v245, 51
	global_load_dwordx4 v[52:55], v[4:5], off
	s_nop 0
	v_lshl_add_u64 v[4:5], v[2:3], 0, s[24:25]
	v_readlane_b32 s24, v245, 52
	v_readlane_b32 s25, v245, 53
	global_load_dwordx4 v[48:51], v[4:5], off
	s_nop 0
	v_lshl_add_u64 v[4:5], v[2:3], 0, s[24:25]
	v_readlane_b32 s24, v245, 54
	v_readlane_b32 s25, v245, 55
	global_load_dwordx4 v[44:47], v[4:5], off
	s_nop 0
	v_lshl_add_u64 v[4:5], v[2:3], 0, s[24:25]
	v_readlane_b32 s24, v245, 56
	v_readlane_b32 s25, v245, 57
	global_load_dwordx4 v[40:43], v[4:5], off
	s_nop 0
	v_lshl_add_u64 v[4:5], v[2:3], 0, s[24:25]
	v_readlane_b32 s24, v245, 60
	v_readlane_b32 s25, v245, 61
	global_load_dwordx4 v[36:39], v[4:5], off
	s_nop 0
	v_lshl_add_u64 v[2:3], v[2:3], 0, s[24:25]
	global_load_dwordx4 v[32:35], v[2:3], off
	v_mad_u64_u32 v[2:3], s[24:25], v138, s26, v[0:1]
	v_add_u32_e32 v3, s5, v3
	v_lshl_add_u64 v[2:3], v[2:3], 0, s[0:1]
	v_mad_u64_u32 v[0:1], s[24:25], v128, s26, v[0:1]
	v_lshl_add_u64 v[2:3], v[2:3], 0, s[8:9]
	v_add_u32_e32 v1, s5, v1
	v_lshl_add_u64 v[2:3], v[2:3], 0, v[116:117]
	v_lshl_add_u64 v[0:1], v[0:1], 0, s[0:1]
	v_lshl_add_u64 v[4:5], v[2:3], 0, s[80:81]
	v_add_co_u32_e32 v2, vcc, s11, v2
	v_lshl_add_u64 v[0:1], v[0:1], 0, s[8:9]
	v_readfirstlane_b32 s0, v89
	v_addc_co_u32_e32 v3, vcc, 0, v3, vcc
	v_lshl_add_u64 v[0:1], v[0:1], 0, v[116:117]
	s_ashr_i32 s1, s0, 3
	s_lshr_b32 s0, s0, 1
	global_load_dwordx2 v[136:137], v[2:3], off
	global_load_dwordx2 v[134:135], v[4:5], off offset:16
	global_load_dwordx2 v[132:133], v[4:5], off offset:32
	global_load_dwordx2 v[130:131], v[4:5], off offset:48
	v_lshl_add_u64 v[2:3], v[0:1], 0, s[80:81]
	v_add_co_u32_e32 v0, vcc, s11, v0
	s_and_b32 s11, s0, 0x60
	v_or_b32_e32 v4, s3, v88
	v_or_b32_e32 v16, s11, v4
	v_lshlrev_b32_e32 v4, 5, v16
	v_mov_b32_e32 v5, v193
	v_addc_co_u32_e32 v1, vcc, 0, v1, vcc
	v_lshl_add_u64 v[4:5], v[106:107], 0, v[4:5]
	global_load_dwordx2 v[126:127], v[0:1], off
	global_load_dwordx2 v[124:125], v[2:3], off offset:16
	global_load_dwordx2 v[122:123], v[2:3], off offset:32
	global_load_dwordx2 v[120:121], v[2:3], off offset:48
	s_waitcnt lgkmcnt(0)
	s_barrier
	s_and_b32 s5, s1, 0xffffffe0
	v_readlane_b32 s0, v245, 38
	v_lshlrev_b32_e32 v16, 2, v16
	v_readlane_b32 s1, v245, 39
	v_or_b32_e32 v0, s5, v88
	v_lshl_add_u32 v0, v0, 5, v145
	ds_read_b128 v[0:3], v0
	s_mov_b32 s3, 0xbfb8aa3b
	s_mov_b32 s24, 0x3f317217
	s_mov_b32 s25, 0x7f800000
	s_waitcnt vmcnt(16) lgkmcnt(0)
	v_mfma_f32_32x32x16_bf16 v[0:15], v[0:3], v[216:219], 0
	v_mov_b32_e32 v16, v223
	s_nop 10
	v_add_f32_e32 v0, v16, v0
	v_min_f32_e32 v17, 0, v0
	v_mul_f32_e64 v0, |v0|, s3
	v_exp_f32_e32 v0, v0
	v_add_f32_e32 v1, v16, v1
	v_add_f32_e32 v0, 1.0, v0
	v_cmp_gt_f32_e32 vcc, s83, v0
	s_nop 1
	v_cndmask_b32_e64 v18, 0, 32, vcc
	v_ldexp_f32 v0, v0, v18
	v_log_f32_e32 v0, v0
	s_nop 0
	v_mul_f32_e32 v18, 0x3f317217, v0
	v_fma_f32 v18, v0, s24, -v18
	v_fmac_f32_e32 v18, 0x3377d1cf, v0
	v_fmac_f32_e32 v18, 0x3f317217, v0
	v_cmp_lt_f32_e64 s[0:1], |v0|, s25
	s_nop 1
	v_cndmask_b32_e64 v0, v0, v18, s[0:1]
	v_cndmask_b32_e32 v18, 0, v211, vcc
	v_sub_f32_e32 v0, v0, v18
	v_min_f32_e32 v18, 0, v1
	v_mul_f32_e64 v1, |v1|, s3
	v_exp_f32_e32 v1, v1
	s_lshl_b32 s0, s5, 9
	s_lshl_b32 s1, s11, 2
	v_sub_f32_e32 v0, v17, v0
	v_add_f32_e32 v1, 1.0, v1
	v_cmp_gt_f32_e32 vcc, s83, v1
	s_or_b32 s0, s0, s1
	v_mul_f32_e32 v17, 0x3d800000, v0
	v_cndmask_b32_e64 v19, 0, 32, vcc
	v_ldexp_f32 v1, v1, v19
	v_log_f32_e32 v1, v1
	v_add_u32_e32 v0, s0, v146
	v_mul_f32_e32 v19, 0x3f317217, v1
	v_fma_f32 v19, v1, s24, -v19
	v_fmac_f32_e32 v19, 0x3377d1cf, v1
	v_fmac_f32_e32 v19, 0x3f317217, v1
	v_cmp_lt_f32_e64 s[0:1], |v1|, s25
	s_nop 1
	v_cndmask_b32_e64 v1, v1, v19, s[0:1]
	v_cndmask_b32_e32 v19, 0, v211, vcc
	v_sub_f32_e32 v1, v1, v19
	v_sub_f32_e32 v1, v18, v1
	v_mul_f32_e32 v1, 0x3d800000, v1
	ds_write2st64_b32 v0, v17, v1 offset0:176 offset1:178
	v_add_f32_e32 v1, v16, v2
	v_min_f32_e32 v2, 0, v1
	v_mul_f32_e64 v1, |v1|, s3
	v_exp_f32_e32 v1, v1
	s_nop 0
	v_add_f32_e32 v1, 1.0, v1
	v_cmp_gt_f32_e32 vcc, s83, v1
	s_nop 1
	v_cndmask_b32_e64 v17, 0, 32, vcc
	v_ldexp_f32 v1, v1, v17
	v_log_f32_e32 v1, v1
	s_nop 0
	v_mul_f32_e32 v17, 0x3f317217, v1
	v_fma_f32 v17, v1, s24, -v17
	v_fmac_f32_e32 v17, 0x3377d1cf, v1
	v_fmac_f32_e32 v17, 0x3f317217, v1
	v_cmp_lt_f32_e64 s[0:1], |v1|, s25
	s_nop 1
	v_cndmask_b32_e64 v1, v1, v17, s[0:1]
	v_cndmask_b32_e32 v17, 0, v211, vcc
	v_sub_f32_e32 v1, v1, v17
	v_sub_f32_e32 v1, v2, v1
	v_add_f32_e32 v2, v16, v3
	v_min_f32_e32 v3, 0, v2
	v_mul_f32_e64 v2, |v2|, s3
	v_exp_f32_e32 v2, v2
	v_mul_f32_e32 v1, 0x3d800000, v1
	v_add_f32_e32 v2, 1.0, v2
	v_cmp_gt_f32_e32 vcc, s83, v2
	s_nop 1
	v_cndmask_b32_e64 v17, 0, 32, vcc
	v_ldexp_f32 v2, v2, v17
	v_log_f32_e32 v2, v2
	s_nop 0
	v_mul_f32_e32 v17, 0x3f317217, v2
	v_fma_f32 v17, v2, s24, -v17
	v_fmac_f32_e32 v17, 0x3377d1cf, v2
	v_fmac_f32_e32 v17, 0x3f317217, v2
	v_cmp_lt_f32_e64 s[0:1], |v2|, s25
	s_nop 1
	v_cndmask_b32_e64 v2, v2, v17, s[0:1]
	v_cndmask_b32_e32 v17, 0, v211, vcc
	v_sub_f32_e32 v2, v2, v17
	v_sub_f32_e32 v2, v3, v2
	v_mul_f32_e32 v2, 0x3d800000, v2
	ds_write2st64_b32 v0, v1, v2 offset0:180 offset1:182
	v_add_f32_e32 v1, v16, v4
	v_min_f32_e32 v2, 0, v1
	v_mul_f32_e64 v1, |v1|, s3
	v_exp_f32_e32 v1, v1
	s_nop 0
	v_add_f32_e32 v1, 1.0, v1
	v_cmp_gt_f32_e32 vcc, s83, v1
	s_nop 1
	v_cndmask_b32_e64 v3, 0, 32, vcc
	v_ldexp_f32 v1, v1, v3
	v_log_f32_e32 v1, v1
	s_nop 0
	v_mul_f32_e32 v3, 0x3f317217, v1
	v_fma_f32 v3, v1, s24, -v3
	v_fmac_f32_e32 v3, 0x3377d1cf, v1
	v_fmac_f32_e32 v3, 0x3f317217, v1
	v_cmp_lt_f32_e64 s[0:1], |v1|, s25
	s_nop 1
	v_cndmask_b32_e64 v1, v1, v3, s[0:1]
	v_cndmask_b32_e32 v3, 0, v211, vcc
	v_sub_f32_e32 v1, v1, v3
	v_sub_f32_e32 v1, v2, v1
	v_add_f32_e32 v2, v16, v5
	v_min_f32_e32 v3, 0, v2
	v_mul_f32_e64 v2, |v2|, s3
	v_exp_f32_e32 v2, v2
	v_mul_f32_e32 v1, 0x3d800000, v1
	v_add_f32_e32 v2, 1.0, v2
	v_cmp_gt_f32_e32 vcc, s83, v2
	s_nop 1
	v_cndmask_b32_e64 v4, 0, 32, vcc
	v_ldexp_f32 v2, v2, v4
	v_log_f32_e32 v2, v2
	s_nop 0
	v_mul_f32_e32 v4, 0x3f317217, v2
	v_fma_f32 v4, v2, s24, -v4
	v_fmac_f32_e32 v4, 0x3377d1cf, v2
	v_fmac_f32_e32 v4, 0x3f317217, v2
	v_cmp_lt_f32_e64 s[0:1], |v2|, s25
	s_nop 1
	v_cndmask_b32_e64 v2, v2, v4, s[0:1]
	v_cndmask_b32_e32 v4, 0, v211, vcc
	v_sub_f32_e32 v2, v2, v4
	v_sub_f32_e32 v2, v3, v2
	v_mul_f32_e32 v2, 0x3d800000, v2
	ds_write2st64_b32 v0, v1, v2 offset0:192 offset1:194
	v_add_f32_e32 v1, v16, v6
	v_min_f32_e32 v2, 0, v1
	v_mul_f32_e64 v1, |v1|, s3
	v_exp_f32_e32 v1, v1
	s_nop 0
	v_add_f32_e32 v1, 1.0, v1
	v_cmp_gt_f32_e32 vcc, s83, v1
	s_nop 1
	v_cndmask_b32_e64 v3, 0, 32, vcc
	v_ldexp_f32 v1, v1, v3
	v_log_f32_e32 v1, v1
	s_nop 0
	v_mul_f32_e32 v3, 0x3f317217, v1
	v_fma_f32 v3, v1, s24, -v3
	v_fmac_f32_e32 v3, 0x3377d1cf, v1
	v_fmac_f32_e32 v3, 0x3f317217, v1
	v_cmp_lt_f32_e64 s[0:1], |v1|, s25
	s_nop 1
	v_cndmask_b32_e64 v1, v1, v3, s[0:1]
	v_cndmask_b32_e32 v3, 0, v211, vcc
	v_sub_f32_e32 v1, v1, v3
	v_sub_f32_e32 v1, v2, v1
	v_add_f32_e32 v2, v16, v7
	v_min_f32_e32 v3, 0, v2
	v_mul_f32_e64 v2, |v2|, s3
	v_exp_f32_e32 v2, v2
	v_mul_f32_e32 v1, 0x3d800000, v1
	v_add_f32_e32 v2, 1.0, v2
	v_cmp_gt_f32_e32 vcc, s83, v2
	s_nop 1
	v_cndmask_b32_e64 v4, 0, 32, vcc
	v_ldexp_f32 v2, v2, v4
	v_log_f32_e32 v2, v2
	s_nop 0
	v_mul_f32_e32 v4, 0x3f317217, v2
	v_fma_f32 v4, v2, s24, -v4
	v_fmac_f32_e32 v4, 0x3377d1cf, v2
	v_fmac_f32_e32 v4, 0x3f317217, v2
	v_cmp_lt_f32_e64 s[0:1], |v2|, s25
	s_nop 1
	v_cndmask_b32_e64 v2, v2, v4, s[0:1]
	v_cndmask_b32_e32 v4, 0, v211, vcc
	v_sub_f32_e32 v2, v2, v4
	v_sub_f32_e32 v2, v3, v2
	v_mul_f32_e32 v2, 0x3d800000, v2
	ds_write2st64_b32 v0, v1, v2 offset0:196 offset1:198
	v_add_f32_e32 v1, v16, v8
	v_min_f32_e32 v2, 0, v1
	v_mul_f32_e64 v1, |v1|, s3
	v_exp_f32_e32 v1, v1
	s_nop 0
	v_add_f32_e32 v1, 1.0, v1
	v_cmp_gt_f32_e32 vcc, s83, v1
	s_nop 1
	v_cndmask_b32_e64 v3, 0, 32, vcc
	v_ldexp_f32 v1, v1, v3
	v_log_f32_e32 v1, v1
	s_nop 0
	v_mul_f32_e32 v3, 0x3f317217, v1
	v_fma_f32 v3, v1, s24, -v3
	v_fmac_f32_e32 v3, 0x3377d1cf, v1
	v_fmac_f32_e32 v3, 0x3f317217, v1
	v_cmp_lt_f32_e64 s[0:1], |v1|, s25
	s_nop 1
	v_cndmask_b32_e64 v1, v1, v3, s[0:1]
	v_cndmask_b32_e32 v3, 0, v211, vcc
	v_sub_f32_e32 v1, v1, v3
	v_sub_f32_e32 v1, v2, v1
	v_add_f32_e32 v2, v16, v9
	v_min_f32_e32 v3, 0, v2
	v_mul_f32_e64 v2, |v2|, s3
	v_exp_f32_e32 v2, v2
	v_mul_f32_e32 v1, 0x3d800000, v1
	v_add_f32_e32 v2, 1.0, v2
	v_cmp_gt_f32_e32 vcc, s83, v2
	s_nop 1
	v_cndmask_b32_e64 v4, 0, 32, vcc
	v_ldexp_f32 v2, v2, v4
	v_log_f32_e32 v2, v2
	s_nop 0
	v_mul_f32_e32 v4, 0x3f317217, v2
	v_fma_f32 v4, v2, s24, -v4
	v_fmac_f32_e32 v4, 0x3377d1cf, v2
	v_fmac_f32_e32 v4, 0x3f317217, v2
	v_cmp_lt_f32_e64 s[0:1], |v2|, s25
	s_nop 1
	v_cndmask_b32_e64 v2, v2, v4, s[0:1]
	v_cndmask_b32_e32 v4, 0, v211, vcc
	v_sub_f32_e32 v2, v2, v4
	v_sub_f32_e32 v2, v3, v2
	v_mul_f32_e32 v2, 0x3d800000, v2
	ds_write2st64_b32 v0, v1, v2 offset0:208 offset1:210
	v_add_f32_e32 v1, v16, v10
	v_min_f32_e32 v2, 0, v1
	v_mul_f32_e64 v1, |v1|, s3
	v_exp_f32_e32 v1, v1
	s_nop 0
	v_add_f32_e32 v1, 1.0, v1
	v_cmp_gt_f32_e32 vcc, s83, v1
	s_nop 1
	v_cndmask_b32_e64 v3, 0, 32, vcc
	v_ldexp_f32 v1, v1, v3
	v_log_f32_e32 v1, v1
	s_nop 0
	v_mul_f32_e32 v3, 0x3f317217, v1
	v_fma_f32 v3, v1, s24, -v3
	v_fmac_f32_e32 v3, 0x3377d1cf, v1
	v_fmac_f32_e32 v3, 0x3f317217, v1
	v_cmp_lt_f32_e64 s[0:1], |v1|, s25
	s_nop 1
	v_cndmask_b32_e64 v1, v1, v3, s[0:1]
	v_cndmask_b32_e32 v3, 0, v211, vcc
	v_sub_f32_e32 v1, v1, v3
	v_sub_f32_e32 v1, v2, v1
	v_add_f32_e32 v2, v16, v11
	v_min_f32_e32 v3, 0, v2
	v_mul_f32_e64 v2, |v2|, s3
	v_exp_f32_e32 v2, v2
	v_mul_f32_e32 v1, 0x3d800000, v1
	v_add_f32_e32 v2, 1.0, v2
	v_cmp_gt_f32_e32 vcc, s83, v2
	s_nop 1
	v_cndmask_b32_e64 v4, 0, 32, vcc
	v_ldexp_f32 v2, v2, v4
	v_log_f32_e32 v2, v2
	s_nop 0
	v_mul_f32_e32 v4, 0x3f317217, v2
	v_fma_f32 v4, v2, s24, -v4
	v_fmac_f32_e32 v4, 0x3377d1cf, v2
	v_fmac_f32_e32 v4, 0x3f317217, v2
	v_cmp_lt_f32_e64 s[0:1], |v2|, s25
	s_nop 1
	v_cndmask_b32_e64 v2, v2, v4, s[0:1]
	v_cndmask_b32_e32 v4, 0, v211, vcc
	v_sub_f32_e32 v2, v2, v4
	v_sub_f32_e32 v2, v3, v2
	v_mul_f32_e32 v2, 0x3d800000, v2
	ds_write2st64_b32 v0, v1, v2 offset0:212 offset1:214
	v_add_f32_e32 v1, v16, v12
	v_min_f32_e32 v2, 0, v1
	v_mul_f32_e64 v1, |v1|, s3
	v_exp_f32_e32 v1, v1
	s_nop 0
	v_add_f32_e32 v1, 1.0, v1
	v_cmp_gt_f32_e32 vcc, s83, v1
	s_nop 1
	v_cndmask_b32_e64 v3, 0, 32, vcc
	v_ldexp_f32 v1, v1, v3
	v_log_f32_e32 v1, v1
	s_nop 0
	v_mul_f32_e32 v3, 0x3f317217, v1
	v_fma_f32 v3, v1, s24, -v3
	v_fmac_f32_e32 v3, 0x3377d1cf, v1
	v_fmac_f32_e32 v3, 0x3f317217, v1
	v_cmp_lt_f32_e64 s[0:1], |v1|, s25
	s_nop 1
	v_cndmask_b32_e64 v1, v1, v3, s[0:1]
	v_cndmask_b32_e32 v3, 0, v211, vcc
	v_sub_f32_e32 v1, v1, v3
	v_sub_f32_e32 v1, v2, v1
	v_add_f32_e32 v2, v16, v13
	v_min_f32_e32 v3, 0, v2
	v_mul_f32_e64 v2, |v2|, s3
	v_exp_f32_e32 v2, v2
	v_mul_f32_e32 v1, 0x3d800000, v1
	v_add_f32_e32 v2, 1.0, v2
	v_cmp_gt_f32_e32 vcc, s83, v2
	s_nop 1
	v_cndmask_b32_e64 v4, 0, 32, vcc
	v_ldexp_f32 v2, v2, v4
	v_log_f32_e32 v2, v2
	s_nop 0
	v_mul_f32_e32 v4, 0x3f317217, v2
	v_fma_f32 v4, v2, s24, -v4
	v_fmac_f32_e32 v4, 0x3377d1cf, v2
	v_fmac_f32_e32 v4, 0x3f317217, v2
	v_cmp_lt_f32_e64 s[0:1], |v2|, s25
	s_nop 1
	v_cndmask_b32_e64 v2, v2, v4, s[0:1]
	v_cndmask_b32_e32 v4, 0, v211, vcc
	v_sub_f32_e32 v2, v2, v4
	v_sub_f32_e32 v2, v3, v2
	v_mul_f32_e32 v2, 0x3d800000, v2
	ds_write2st64_b32 v0, v1, v2 offset0:224 offset1:226
	v_add_f32_e32 v1, v16, v14
	v_min_f32_e32 v2, 0, v1
	v_mul_f32_e64 v1, |v1|, s3
	v_exp_f32_e32 v1, v1
	s_nop 0
	v_add_f32_e32 v1, 1.0, v1
	v_cmp_gt_f32_e32 vcc, s83, v1
	s_nop 1
	v_cndmask_b32_e64 v3, 0, 32, vcc
	v_ldexp_f32 v1, v1, v3
	v_log_f32_e32 v1, v1
	s_nop 0
	v_mul_f32_e32 v3, 0x3f317217, v1
	v_fma_f32 v3, v1, s24, -v3
	v_fmac_f32_e32 v3, 0x3377d1cf, v1
	v_fmac_f32_e32 v3, 0x3f317217, v1
	v_cmp_lt_f32_e64 s[0:1], |v1|, s25
	s_nop 1
	v_cndmask_b32_e64 v1, v1, v3, s[0:1]
	v_cndmask_b32_e32 v3, 0, v211, vcc
	v_sub_f32_e32 v1, v1, v3
	v_sub_f32_e32 v1, v2, v1
	v_add_f32_e32 v2, v16, v15
	v_min_f32_e32 v3, 0, v2
	v_mul_f32_e64 v2, |v2|, s3
	v_exp_f32_e32 v2, v2
	v_mul_f32_e32 v1, 0x3d800000, v1
	v_add_f32_e32 v2, 1.0, v2
	v_cmp_gt_f32_e32 vcc, s83, v2
	s_nop 1
	v_cndmask_b32_e64 v4, 0, 32, vcc
	v_ldexp_f32 v2, v2, v4
	v_log_f32_e32 v2, v2
	s_nop 0
	v_mul_f32_e32 v4, 0x3f317217, v2
	v_fma_f32 v4, v2, s24, -v4
	v_fmac_f32_e32 v4, 0x3377d1cf, v2
	v_fmac_f32_e32 v4, 0x3f317217, v2
	v_cmp_lt_f32_e64 s[0:1], |v2|, s25
	v_readlane_b32 s24, v244, 0
	v_readlane_b32 s25, v244, 1
	v_cndmask_b32_e64 v2, v2, v4, s[0:1]
	v_cndmask_b32_e32 v4, 0, v211, vcc
	v_sub_f32_e32 v2, v2, v4
	v_sub_f32_e32 v2, v3, v2
	v_mul_f32_e32 v2, 0x3d800000, v2
	ds_write2st64_b32 v0, v1, v2 offset0:228 offset1:230
	s_waitcnt lgkmcnt(0)
	s_barrier
	s_waitcnt vmcnt(0)
	ds_read2st64_b32 v[0:1], v155 offset0:176 offset1:178
	v_readlane_b32 s0, v245, 36
	v_readlane_b32 s1, v245, 37
	s_waitcnt lgkmcnt(0)
	v_add_f32_e32 v2, 0, v0
	v_add_f32_e32 v3, v2, v1
	ds_read2st64_b32 v[0:1], v155 offset0:180 offset1:182
	s_waitcnt lgkmcnt(0)
	v_add_f32_e32 v4, v3, v0
	v_add_f32_e32 v5, v4, v1
	ds_read2st64_b32 v[0:1], v155 offset0:184 offset1:186
	s_waitcnt lgkmcnt(0)
	v_add_f32_e32 v6, v5, v0
	v_add_f32_e32 v7, v6, v1
	ds_read2st64_b32 v[0:1], v155 offset0:188 offset1:190
	s_waitcnt lgkmcnt(0)
	v_add_f32_e32 v8, v7, v0
	v_add_f32_e32 v9, v8, v1
	ds_read2st64_b32 v[0:1], v155 offset0:192 offset1:194
	s_waitcnt lgkmcnt(0)
	v_add_f32_e32 v10, v9, v0
	v_add_f32_e32 v11, v10, v1
	ds_read2st64_b32 v[0:1], v155 offset0:196 offset1:198
	s_waitcnt lgkmcnt(0)
	v_add_f32_e32 v12, v11, v0
	v_add_f32_e32 v13, v12, v1
	ds_read2st64_b32 v[0:1], v155 offset0:200 offset1:202
	s_waitcnt lgkmcnt(0)
	v_add_f32_e32 v14, v13, v0
	v_add_f32_e32 v15, v14, v1
	ds_read2st64_b32 v[0:1], v155 offset0:204 offset1:206
	s_waitcnt lgkmcnt(0)
	v_add_f32_e32 v16, v15, v0
	v_add_f32_e32 v17, v16, v1
	ds_write_b32 v156, v17 offset:4096
	s_waitcnt lgkmcnt(0)
	s_barrier
	ds_read2st64_b32 v[0:1], v140 offset0:16 offset1:18
	s_waitcnt lgkmcnt(0)
	v_add_f32_e32 v0, 0, v0
	v_cndmask_b32_e64 v0, 0, v0, s[0:1]
	v_readlane_b32 s0, v245, 31
	v_add_f32_e32 v1, v1, v0
	v_readlane_b32 s1, v245, 32
	s_nop 1
	v_cndmask_b32_e64 v18, v0, v1, s[0:1]
	ds_read2st64_b32 v[0:1], v140 offset0:20 offset1:22
	v_readlane_b32 s0, v245, 40
	v_readlane_b32 s1, v245, 41
	s_waitcnt lgkmcnt(0)
	v_add_f32_e32 v0, v0, v18
	v_cndmask_b32_e64 v0, v18, v0, s[0:1]
	v_readlane_b32 s0, v245, 42
	v_add_f32_e32 v1, v1, v0
	v_readlane_b32 s1, v245, 43
	s_nop 1
	v_cndmask_b32_e64 v0, v0, v1, s[0:1]
	v_add_f32_e32 v23, v8, v0
	v_add_f32_e32 v8, v10, v0
	ds_read_u16 v10, v157
	v_add_f32_e32 v1, v2, v0
	v_add_f32_e32 v22, v7, v0
	v_add_f32_e32 v7, v11, v0
	v_mul_f32_e32 v11, 0x3fb8aa3b, v1
	v_exp_f32_e32 v11, v11
	s_waitcnt lgkmcnt(0)
	v_lshlrev_b32_e32 v10, 16, v10
	v_mul_f32_e32 v10, 0x3db504f3, v10
	v_mul_f32_e32 v1, 0xbfb8aa3b, v1
	v_mul_f32_e32 v10, v10, v11
	ds_read_u16 v11, v158
	v_exp_f32_e32 v1, v1
	s_movk_i32 s0, 0x7fff
	v_add_f32_e32 v18, v3, v0
	v_add_f32_e32 v21, v6, v0
	s_waitcnt lgkmcnt(0)
	v_lshlrev_b32_e32 v11, 16, v11
	v_mul_f32_e32 v11, v1, v11
	v_bfe_u32 v1, v10, 16, 1
	v_add3_u32 v10, v10, v1, s0
	v_add_u32_e32 v1, v147, v149
	ds_write_b16_d16_hi v1, v10 offset:45056
	v_bfe_u32 v10, v11, 16, 1
	v_add3_u32 v10, v11, v10, s0
	ds_write_b16_d16_hi v1, v10 offset:62464
	ds_read_u16 v10, v157 offset:256
	v_mul_f32_e32 v11, 0x3fb8aa3b, v18
	v_exp_f32_e32 v11, v11
	v_add_f32_e32 v6, v12, v0
	v_mul_f32_e32 v12, 0xbfb8aa3b, v18
	s_waitcnt lgkmcnt(0)
	v_lshlrev_b32_e32 v10, 16, v10
	v_mul_f32_e32 v10, 0x3db504f3, v10
	v_mul_f32_e32 v10, v11, v10
	ds_read_u16 v11, v158 offset:256
	v_exp_f32_e32 v12, v12
	v_add_f32_e32 v19, v4, v0
	v_add_f32_e32 v20, v5, v0
	v_add_f32_e32 v9, v9, v0
	s_waitcnt lgkmcnt(0)
	v_lshlrev_b32_e32 v11, 16, v11
	v_mul_f32_e32 v11, v12, v11
	v_bfe_u32 v12, v10, 16, 1
	v_add3_u32 v10, v10, v12, s0
	ds_write_b16_d16_hi v1, v10 offset:45328
	v_bfe_u32 v10, v11, 16, 1
	v_add3_u32 v10, v11, v10, s0
	ds_write_b16_d16_hi v1, v10 offset:62736
	ds_read_u16 v10, v157 offset:512
	v_mul_f32_e32 v11, 0x3fb8aa3b, v19
	v_exp_f32_e32 v11, v11
	v_mul_f32_e32 v12, 0xbfb8aa3b, v19
	v_exp_f32_e32 v12, v12
	s_waitcnt lgkmcnt(0)
	v_lshlrev_b32_e32 v10, 16, v10
	v_mul_f32_e32 v10, 0x3db504f3, v10
	v_mul_f32_e32 v10, v11, v10
	ds_read_u16 v11, v158 offset:512
	v_add_f32_e32 v5, v13, v0
	v_add_f32_e32 v4, v14, v0
	v_add_f32_e32 v3, v15, v0
	v_add_f32_e32 v2, v16, v0
	s_waitcnt lgkmcnt(0)
	v_lshlrev_b32_e32 v11, 16, v11
	v_mul_f32_e32 v11, v12, v11
	v_bfe_u32 v12, v10, 16, 1
	v_add3_u32 v10, v10, v12, s0
	ds_write_b16_d16_hi v1, v10 offset:45600
	v_bfe_u32 v10, v11, 16, 1
	v_add3_u32 v10, v11, v10, s0
	ds_write_b16_d16_hi v1, v10 offset:63008
	ds_read_u16 v10, v157 offset:768
	v_mul_f32_e32 v11, 0x3fb8aa3b, v20
	v_exp_f32_e32 v11, v11
	v_mul_f32_e32 v12, 0xbfb8aa3b, v20
	v_exp_f32_e32 v12, v12
	s_waitcnt lgkmcnt(0)
	v_lshlrev_b32_e32 v10, 16, v10
	v_mul_f32_e32 v10, 0x3db504f3, v10
	v_mul_f32_e32 v10, v11, v10
	ds_read_u16 v11, v158 offset:768
	v_add_f32_e32 v0, v17, v0
	s_waitcnt lgkmcnt(0)
	v_lshlrev_b32_e32 v11, 16, v11
	v_mul_f32_e32 v11, v12, v11
	v_bfe_u32 v12, v10, 16, 1
	v_add3_u32 v10, v10, v12, s0
	ds_write_b16_d16_hi v1, v10 offset:45872
	v_bfe_u32 v10, v11, 16, 1
	v_add3_u32 v10, v11, v10, s0
	ds_write_b16_d16_hi v1, v10 offset:63280
	ds_read_u16 v10, v157 offset:1024
	v_mul_f32_e32 v11, 0x3fb8aa3b, v21
	v_exp_f32_e32 v11, v11
	v_mul_f32_e32 v12, 0xbfb8aa3b, v21
	v_exp_f32_e32 v12, v12
	s_waitcnt lgkmcnt(0)
	v_lshlrev_b32_e32 v10, 16, v10
	v_mul_f32_e32 v10, 0x3db504f3, v10
	v_mul_f32_e32 v10, v11, v10
	ds_read_u16 v11, v158 offset:1024
	s_waitcnt lgkmcnt(0)
	v_lshlrev_b32_e32 v11, 16, v11
	v_mul_f32_e32 v11, v12, v11
	v_bfe_u32 v12, v10, 16, 1
	v_add3_u32 v10, v10, v12, s0
	ds_write_b16_d16_hi v1, v10 offset:46144
	v_bfe_u32 v10, v11, 16, 1
	v_add3_u32 v10, v11, v10, s0
	ds_write_b16_d16_hi v1, v10 offset:63552
	ds_read_u16 v10, v157 offset:1280
	v_mul_f32_e32 v11, 0x3fb8aa3b, v22
	v_exp_f32_e32 v11, v11
	v_mul_f32_e32 v12, 0xbfb8aa3b, v22
	v_exp_f32_e32 v12, v12
	s_waitcnt lgkmcnt(0)
	v_lshlrev_b32_e32 v10, 16, v10
	v_mul_f32_e32 v10, 0x3db504f3, v10
	v_mul_f32_e32 v10, v11, v10
	ds_read_u16 v11, v158 offset:1280
	s_waitcnt lgkmcnt(0)
	v_lshlrev_b32_e32 v11, 16, v11
	v_mul_f32_e32 v11, v12, v11
	v_bfe_u32 v12, v10, 16, 1
	v_add3_u32 v10, v10, v12, s0
	ds_write_b16_d16_hi v1, v10 offset:46416
	v_bfe_u32 v10, v11, 16, 1
	v_add3_u32 v10, v11, v10, s0
	ds_write_b16_d16_hi v1, v10 offset:63824
	ds_read_u16 v10, v157 offset:1536
	v_mul_f32_e32 v11, 0x3fb8aa3b, v23
	v_exp_f32_e32 v11, v11
	v_mul_f32_e32 v12, 0xbfb8aa3b, v23
	v_exp_f32_e32 v12, v12
	s_waitcnt lgkmcnt(0)
	v_lshlrev_b32_e32 v10, 16, v10
	v_mul_f32_e32 v10, 0x3db504f3, v10
	v_mul_f32_e32 v10, v11, v10
	ds_read_u16 v11, v158 offset:1536
	s_waitcnt lgkmcnt(0)
	v_lshlrev_b32_e32 v11, 16, v11
	v_mul_f32_e32 v11, v12, v11
	v_bfe_u32 v12, v10, 16, 1
	v_add3_u32 v10, v10, v12, s0
	ds_write_b16_d16_hi v1, v10 offset:46688
	v_bfe_u32 v10, v11, 16, 1
	v_add3_u32 v10, v11, v10, s0
	ds_write_b16_d16_hi v1, v10 offset:64096
	ds_read_u16 v10, v157 offset:1792
	v_mul_f32_e32 v11, 0x3fb8aa3b, v9
	v_exp_f32_e32 v11, v11
	v_mul_f32_e32 v9, 0xbfb8aa3b, v9
	v_exp_f32_e32 v9, v9
	s_waitcnt lgkmcnt(0)
	v_lshlrev_b32_e32 v10, 16, v10
	v_mul_f32_e32 v10, 0x3db504f3, v10
	v_mul_f32_e32 v10, v11, v10
	ds_read_u16 v11, v158 offset:1792
	s_waitcnt lgkmcnt(0)
	v_lshlrev_b32_e32 v11, 16, v11
	v_mul_f32_e32 v9, v9, v11
	v_bfe_u32 v11, v10, 16, 1
	v_add3_u32 v10, v10, v11, s0
	ds_write_b16_d16_hi v1, v10 offset:46960
	v_bfe_u32 v10, v9, 16, 1
	v_add3_u32 v9, v9, v10, s0
	ds_write_b16_d16_hi v1, v9 offset:64368
	ds_read_u16 v9, v157 offset:2048
	v_mul_f32_e32 v10, 0x3fb8aa3b, v8
	v_exp_f32_e32 v10, v10
	v_mul_f32_e32 v8, 0xbfb8aa3b, v8
	v_exp_f32_e32 v8, v8
	s_waitcnt lgkmcnt(0)
	v_lshlrev_b32_e32 v9, 16, v9
	v_mul_f32_e32 v9, 0x3db504f3, v9
	v_mul_f32_e32 v9, v10, v9
	ds_read_u16 v10, v158 offset:2048
	s_waitcnt lgkmcnt(0)
	v_lshlrev_b32_e32 v10, 16, v10
	v_mul_f32_e32 v8, v8, v10
	v_bfe_u32 v10, v9, 16, 1
	v_add3_u32 v9, v9, v10, s0
	ds_write_b16_d16_hi v1, v9 offset:47232
	v_bfe_u32 v9, v8, 16, 1
	v_add3_u32 v8, v8, v9, s0
	ds_write_b16_d16_hi v1, v8 offset:64640
	ds_read_u16 v8, v157 offset:2304
	v_mul_f32_e32 v9, 0x3fb8aa3b, v7
	v_exp_f32_e32 v9, v9
	v_mul_f32_e32 v7, 0xbfb8aa3b, v7
	v_exp_f32_e32 v7, v7
	s_waitcnt lgkmcnt(0)
	v_lshlrev_b32_e32 v8, 16, v8
	v_mul_f32_e32 v8, 0x3db504f3, v8
	v_mul_f32_e32 v8, v9, v8
	ds_read_u16 v9, v158 offset:2304
	s_waitcnt lgkmcnt(0)
	v_lshlrev_b32_e32 v9, 16, v9
	v_mul_f32_e32 v7, v7, v9
	v_bfe_u32 v9, v8, 16, 1
	v_add3_u32 v8, v8, v9, s0
	ds_write_b16_d16_hi v1, v8 offset:47504
	v_bfe_u32 v8, v7, 16, 1
	v_add3_u32 v7, v7, v8, s0
	ds_write_b16_d16_hi v1, v7 offset:64912
	ds_read_u16 v7, v157 offset:2560
	v_mul_f32_e32 v8, 0x3fb8aa3b, v6
	v_exp_f32_e32 v8, v8
	v_mul_f32_e32 v6, 0xbfb8aa3b, v6
	v_exp_f32_e32 v6, v6
	s_waitcnt lgkmcnt(0)
	v_lshlrev_b32_e32 v7, 16, v7
	v_mul_f32_e32 v7, 0x3db504f3, v7
	v_mul_f32_e32 v7, v8, v7
	ds_read_u16 v8, v158 offset:2560
	s_waitcnt lgkmcnt(0)
	v_lshlrev_b32_e32 v8, 16, v8
	v_mul_f32_e32 v6, v6, v8
	v_bfe_u32 v8, v7, 16, 1
	v_add3_u32 v7, v7, v8, s0
	ds_write_b16_d16_hi v1, v7 offset:47776
	v_bfe_u32 v7, v6, 16, 1
	v_add3_u32 v6, v6, v7, s0
	ds_write_b16_d16_hi v1, v6 offset:65184
	ds_read_u16 v6, v157 offset:2816
	v_mul_f32_e32 v7, 0x3fb8aa3b, v5
	v_exp_f32_e32 v7, v7
	v_mul_f32_e32 v5, 0xbfb8aa3b, v5
	v_exp_f32_e32 v5, v5
	s_waitcnt lgkmcnt(0)
	v_lshlrev_b32_e32 v6, 16, v6
	v_mul_f32_e32 v6, 0x3db504f3, v6
	v_mul_f32_e32 v6, v7, v6
	ds_read_u16 v7, v158 offset:2816
	s_waitcnt lgkmcnt(0)
	v_lshlrev_b32_e32 v7, 16, v7
	v_mul_f32_e32 v5, v5, v7
	v_bfe_u32 v7, v6, 16, 1
	v_add3_u32 v6, v6, v7, s0
	ds_write_b16_d16_hi v1, v6 offset:48048
	v_bfe_u32 v6, v5, 16, 1
	v_add3_u32 v5, v5, v6, s0
	ds_write_b16_d16_hi v1, v5 offset:65456
	ds_read_u16 v5, v157 offset:3072
	v_mul_f32_e32 v6, 0x3fb8aa3b, v4
	v_exp_f32_e32 v6, v6
	v_mul_f32_e32 v4, 0xbfb8aa3b, v4
	v_exp_f32_e32 v4, v4
	s_waitcnt lgkmcnt(0)
	v_lshlrev_b32_e32 v5, 16, v5
	v_mul_f32_e32 v5, 0x3db504f3, v5
	v_mul_f32_e32 v5, v6, v5
	ds_read_u16 v6, v158 offset:3072
	s_waitcnt lgkmcnt(0)
	v_lshlrev_b32_e32 v6, 16, v6
	v_mul_f32_e32 v4, v4, v6
	v_bfe_u32 v6, v5, 16, 1
	v_add3_u32 v5, v5, v6, s0
	ds_write_b16_d16_hi v1, v5 offset:48320
	v_bfe_u32 v5, v4, 16, 1
	v_add3_u32 v4, v4, v5, s0
	ds_write_b16_d16_hi v159, v4 offset:62464
	ds_read_u16 v4, v157 offset:3328
	v_mul_f32_e32 v5, 0x3fb8aa3b, v3
	v_exp_f32_e32 v5, v5
	v_mul_f32_e32 v3, 0xbfb8aa3b, v3
	v_exp_f32_e32 v3, v3
	s_waitcnt lgkmcnt(0)
	v_lshlrev_b32_e32 v4, 16, v4
	v_mul_f32_e32 v4, 0x3db504f3, v4
	v_mul_f32_e32 v4, v5, v4
	ds_read_u16 v5, v158 offset:3328
	s_waitcnt lgkmcnt(0)
	v_lshlrev_b32_e32 v5, 16, v5
	v_mul_f32_e32 v3, v3, v5
	v_bfe_u32 v5, v4, 16, 1
	v_add3_u32 v4, v4, v5, s0
	ds_write_b16_d16_hi v1, v4 offset:48592
	v_bfe_u32 v4, v3, 16, 1
	v_add3_u32 v3, v3, v4, s0
	ds_write_b16_d16_hi v160, v3 offset:62464
	ds_read_u16 v3, v157 offset:3584
	v_mul_f32_e32 v4, 0x3fb8aa3b, v2
	v_exp_f32_e32 v4, v4
	v_mul_f32_e32 v2, 0xbfb8aa3b, v2
	v_exp_f32_e32 v2, v2
	s_waitcnt lgkmcnt(0)
	v_lshlrev_b32_e32 v3, 16, v3
	v_mul_f32_e32 v3, 0x3db504f3, v3
	v_mul_f32_e32 v3, v4, v3
	ds_read_u16 v4, v158 offset:3584
	s_waitcnt lgkmcnt(0)
	v_lshlrev_b32_e32 v4, 16, v4
	v_mul_f32_e32 v2, v2, v4
	v_bfe_u32 v4, v3, 16, 1
	v_add3_u32 v3, v3, v4, s0
	ds_write_b16_d16_hi v1, v3 offset:48864
	v_bfe_u32 v3, v2, 16, 1
	v_add3_u32 v2, v2, v3, s0
	ds_write_b16_d16_hi v161, v2 offset:62464
	ds_read_u16 v2, v157 offset:3840
	v_mul_f32_e32 v3, 0x3fb8aa3b, v0
	v_exp_f32_e32 v3, v3
	v_mul_f32_e32 v0, 0xbfb8aa3b, v0
	v_exp_f32_e32 v0, v0
	s_waitcnt lgkmcnt(0)
	v_lshlrev_b32_e32 v2, 16, v2
	v_mul_f32_e32 v2, 0x3db504f3, v2
	v_mul_f32_e32 v2, v3, v2
	ds_read_u16 v3, v158 offset:3840
	s_waitcnt lgkmcnt(0)
	v_lshlrev_b32_e32 v3, 16, v3
	v_mul_f32_e32 v0, v0, v3
	v_bfe_u32 v3, v2, 16, 1
	v_add3_u32 v2, v2, v3, s0
	ds_write_b16_d16_hi v1, v2 offset:49136
	v_bfe_u32 v1, v0, 16, 1
	v_add3_u32 v0, v0, v1, s0
	ds_write_b16_d16_hi v162, v0 offset:62464
	s_waitcnt lgkmcnt(0)
	s_barrier
	ds_read_b128 v[16:19], v163 offset:62464
	ds_read_b128 v[0:3], v163 offset:45056
	ds_read_b128 v[20:23], v163 offset:45088
	ds_read_b128 v[24:27], v163 offset:62496
	s_waitcnt lgkmcnt(2)
	v_mfma_f32_32x32x16_bf16 v[0:15], v[16:19], v[0:3], 0
	v_readlane_b32 s0, v245, 62
	v_readlane_b32 s1, v245, 63
	s_waitcnt lgkmcnt(0)
	v_mfma_f32_32x32x16_bf16 v[0:15], v[24:27], v[20:23], v[0:15]
	ds_read_b128 v[20:23], v163 offset:62528
	ds_read_b128 v[28:31], v163 offset:45120
	s_waitcnt lgkmcnt(0)
	v_mfma_f32_32x32x16_bf16 v[0:15], v[20:23], v[28:31], v[0:15]
	ds_read_b128 v[28:31], v163 offset:62560
	ds_read_b128 v[64:67], v163 offset:45152
	s_waitcnt lgkmcnt(0)
	v_mfma_f32_32x32x16_bf16 v[0:15], v[28:31], v[64:67], v[0:15]
	ds_read_b128 v[72:75], v163 offset:62592
	ds_read_b128 v[64:67], v163 offset:45184
	s_waitcnt lgkmcnt(0)
	v_mfma_f32_32x32x16_bf16 v[0:15], v[72:75], v[64:67], v[0:15]
	ds_read_b128 v[76:79], v163 offset:62624
	ds_read_b128 v[64:67], v163 offset:45216
	s_waitcnt lgkmcnt(0)
	v_mfma_f32_32x32x16_bf16 v[0:15], v[76:79], v[64:67], v[0:15]
	ds_read_b128 v[80:83], v163 offset:62656
	ds_read_b128 v[64:67], v163 offset:45248
	s_waitcnt lgkmcnt(0)
	v_mfma_f32_32x32x16_bf16 v[0:15], v[80:83], v[64:67], v[0:15]
	ds_read_b128 v[84:87], v163 offset:62688
	ds_read_b128 v[64:67], v163 offset:45280
	ds_read_b128 v[170:173], v164 offset:45056
	ds_read_b128 v[174:177], v164 offset:45088
	ds_read_b128 v[178:181], v164 offset:45280
	s_waitcnt lgkmcnt(3)
	v_mfma_f32_32x32x16_bf16 v[0:15], v[84:87], v[64:67], v[0:15]
	s_nop 11
	v_cndmask_b32_e64 v64, v0, 0, s[78:79]
	v_cndmask_b32_e64 v0, v64, v0, s[76:77]
	v_cndmask_b32_e64 v1, 0, v1, s[76:77]
	v_cndmask_b32_e64 v2, v2, 0, s[74:75]
	v_cndmask_b32_e64 v3, v3, 0, s[46:47]
	v_cndmask_b32_e64 v4, v4, 0, s[44:45]
	v_cndmask_b32_e64 v5, v5, 0, s[42:43]
	v_cndmask_b32_e64 v6, v6, 0, s[38:39]
	v_cndmask_b32_e64 v7, v7, 0, s[36:37]
	v_cndmask_b32_e64 v8, v8, 0, s[40:41]
	v_cndmask_b32_e64 v9, v9, 0, s[18:19]
	v_cndmask_b32_e64 v10, v10, 0, s[16:17]
	v_cndmask_b32_e64 v11, v11, 0, s[14:15]
	v_cndmask_b32_e64 v12, v12, 0, s[12:13]
	v_cndmask_b32_e64 v13, v13, 0, s[30:31]
	v_cndmask_b32_e64 v14, v14, 0, s[24:25]
	v_cndmask_b32_e64 v15, v15, 0, s[0:1]
	v_cvt_pk_bf16_f32 v68, v0, v1
	v_cvt_pk_bf16_f32 v69, v2, v3
	v_cvt_pk_bf16_f32 v70, v4, v5
	v_cvt_pk_bf16_f32 v71, v6, v7
	v_cvt_pk_bf16_f32 v64, v8, v9
	v_cvt_pk_bf16_f32 v65, v10, v11
	v_cvt_pk_bf16_f32 v66, v12, v13
	v_cvt_pk_bf16_f32 v67, v14, v15
	s_waitcnt lgkmcnt(2)
	v_mfma_f32_32x32x16_bf16 v[0:15], v[16:19], v[170:173], 0
	ds_read_b128 v[16:19], v164 offset:45120
	s_waitcnt lgkmcnt(2)
	v_mfma_f32_32x32x16_bf16 v[0:15], v[24:27], v[174:177], v[0:15]
	ds_read_b128 v[24:27], v164 offset:45184
	s_waitcnt lgkmcnt(1)
	v_mfma_f32_32x32x16_bf16 v[0:15], v[20:23], v[16:19], v[0:15]
	ds_read_b128 v[20:23], v164 offset:45152
	s_waitcnt lgkmcnt(0)
	v_mfma_f32_32x32x16_bf16 v[0:15], v[28:31], v[20:23], v[0:15]
	ds_read_b128 v[28:31], v164 offset:45216
	v_mfma_f32_32x32x16_bf16 v[0:15], v[72:75], v[24:27], v[0:15]
	ds_read_b128 v[72:75], v164 offset:45248
	s_waitcnt lgkmcnt(1)
	v_mfma_f32_32x32x16_bf16 v[0:15], v[76:79], v[28:31], v[0:15]
	s_waitcnt lgkmcnt(0)
	v_mfma_f32_32x32x16_bf16 v[0:15], v[80:83], v[72:75], v[0:15]
	v_mfma_f32_32x32x16_bf16 v[0:15], v[84:87], v[178:181], v[0:15]
	ds_read_b128 v[84:87], v164 offset:62496
	s_nop 10
	v_cvt_pk_bf16_f32 v76, v0, v1
	v_cvt_pk_bf16_f32 v77, v2, v3
	ds_read_b128 v[0:3], v164 offset:62464
	v_cvt_pk_bf16_f32 v78, v4, v5
	v_cvt_pk_bf16_f32 v79, v6, v7
	v_cvt_pk_bf16_f32 v80, v8, v9
	v_cvt_pk_bf16_f32 v81, v10, v11
	v_cvt_pk_bf16_f32 v82, v12, v13
	v_cvt_pk_bf16_f32 v83, v14, v15
	s_waitcnt lgkmcnt(0)
	v_mfma_f32_32x32x16_bf16 v[0:15], v[0:3], v[170:173], 0
	v_mfma_f32_32x32x16_bf16 v[0:15], v[84:87], v[174:177], v[0:15]
	ds_read_b128 v[84:87], v164 offset:62528
	s_waitcnt lgkmcnt(0)
	v_mfma_f32_32x32x16_bf16 v[0:15], v[84:87], v[16:19], v[0:15]
	ds_read_b128 v[16:19], v164 offset:62560
	s_waitcnt lgkmcnt(0)
	v_mfma_f32_32x32x16_bf16 v[0:15], v[16:19], v[20:23], v[0:15]
	ds_read_b128 v[16:19], v164 offset:62592
	s_waitcnt lgkmcnt(0)
	v_mfma_f32_32x32x16_bf16 v[0:15], v[16:19], v[24:27], v[0:15]
	ds_read_b128 v[16:19], v164 offset:62624
	s_waitcnt lgkmcnt(0)
	v_mfma_f32_32x32x16_bf16 v[0:15], v[16:19], v[28:31], v[0:15]
	ds_read_b128 v[16:19], v164 offset:62656
	s_waitcnt lgkmcnt(0)
	v_mfma_f32_32x32x16_bf16 v[0:15], v[16:19], v[72:75], v[0:15]
	ds_read_b128 v[16:19], v164 offset:62688
	s_waitcnt lgkmcnt(0)
	v_mfma_f32_32x32x16_bf16 v[0:15], v[16:19], v[178:181], v[0:15]
	s_nop 11
	v_cndmask_b32_e64 v16, v0, 0, s[78:79]
	v_cndmask_b32_e64 v0, v16, v0, s[76:77]
	v_cndmask_b32_e64 v1, 0, v1, s[76:77]
	v_cndmask_b32_e64 v2, v2, 0, s[74:75]
	v_cndmask_b32_e64 v3, v3, 0, s[46:47]
	v_cvt_pk_bf16_f32 v84, v0, v1
	v_cvt_pk_bf16_f32 v85, v2, v3
	ds_read2_b64 v[0:3], v113 offset1:2
	ds_read2_b64 v[170:173], v113 offset0:4 offset1:6
	s_waitcnt lgkmcnt(1)
	v_mfma_f32_32x32x16_bf16 v[16:31], v[60:63], v[0:3], 0
	ds_read2_b64 v[0:3], v115 offset1:2
	ds_read2_b64 v[174:177], v115 offset0:4 offset1:6
	v_cndmask_b32_e64 v4, v4, 0, s[44:45]
	v_cndmask_b32_e64 v5, v5, 0, s[42:43]
	v_cndmask_b32_e64 v6, v6, 0, s[38:39]
	v_cndmask_b32_e64 v7, v7, 0, s[36:37]
	v_cndmask_b32_e64 v8, v8, 0, s[40:41]
	v_cndmask_b32_e64 v9, v9, 0, s[18:19]
	v_cndmask_b32_e64 v10, v10, 0, s[16:17]
	v_cndmask_b32_e64 v11, v11, 0, s[14:15]
	v_cndmask_b32_e64 v12, v12, 0, s[12:13]
	v_cndmask_b32_e64 v13, v13, 0, s[30:31]
	v_cndmask_b32_e64 v14, v14, 0, s[24:25]
	v_cndmask_b32_e64 v15, v15, 0, s[0:1]
	v_cvt_pk_bf16_f32 v86, v4, v5
	v_cvt_pk_bf16_f32 v87, v6, v7
	v_cvt_pk_bf16_f32 v72, v8, v9
	v_cvt_pk_bf16_f32 v73, v10, v11
	v_cvt_pk_bf16_f32 v74, v12, v13
	v_cvt_pk_bf16_f32 v75, v14, v15
	s_waitcnt lgkmcnt(1)
	v_mfma_f32_32x32x16_bf16 v[0:15], v[60:63], v[0:3], 0
	v_mfma_f32_32x32x16_bf16 v[16:31], v[56:59], v[170:173], v[16:31]
	s_waitcnt lgkmcnt(0)
	v_mfma_f32_32x32x16_bf16 v[0:15], v[56:59], v[174:177], v[0:15]
	ds_read2_b64 v[56:59], v113 offset0:8 offset1:10
	s_waitcnt lgkmcnt(0)
	v_mfma_f32_32x32x16_bf16 v[16:31], v[52:55], v[56:59], v[16:31]
	ds_read2_b64 v[56:59], v115 offset0:8 offset1:10
	s_waitcnt lgkmcnt(0)
	v_mfma_f32_32x32x16_bf16 v[0:15], v[52:55], v[56:59], v[0:15]
	ds_read2_b64 v[52:55], v113 offset0:12 offset1:14
	s_waitcnt lgkmcnt(0)
	v_mfma_f32_32x32x16_bf16 v[16:31], v[48:51], v[52:55], v[16:31]
	ds_read2_b64 v[52:55], v115 offset0:12 offset1:14
	s_waitcnt lgkmcnt(0)
	v_mfma_f32_32x32x16_bf16 v[0:15], v[48:51], v[52:55], v[0:15]
	ds_read2_b64 v[48:51], v113 offset0:16 offset1:18
	s_waitcnt lgkmcnt(0)
	v_mfma_f32_32x32x16_bf16 v[16:31], v[44:47], v[48:51], v[16:31]
	ds_read2_b64 v[48:51], v115 offset0:16 offset1:18
	s_waitcnt lgkmcnt(0)
	v_mfma_f32_32x32x16_bf16 v[0:15], v[44:47], v[48:51], v[0:15]
	ds_read2_b64 v[44:47], v113 offset0:20 offset1:22
	s_waitcnt lgkmcnt(0)
	v_mfma_f32_32x32x16_bf16 v[16:31], v[40:43], v[44:47], v[16:31]
	ds_read2_b64 v[44:47], v115 offset0:20 offset1:22
	s_waitcnt lgkmcnt(0)
	v_mfma_f32_32x32x16_bf16 v[0:15], v[40:43], v[44:47], v[0:15]
	ds_read2_b64 v[40:43], v113 offset0:24 offset1:26
	s_waitcnt lgkmcnt(0)
	v_mfma_f32_32x32x16_bf16 v[16:31], v[36:39], v[40:43], v[16:31]
	ds_read2_b64 v[40:43], v115 offset0:24 offset1:26
	s_waitcnt lgkmcnt(0)
	v_mfma_f32_32x32x16_bf16 v[0:15], v[36:39], v[40:43], v[0:15]
	ds_read2_b64 v[36:39], v113 offset0:28 offset1:30
	s_waitcnt lgkmcnt(0)
	v_mfma_f32_32x32x16_bf16 v[16:31], v[32:35], v[36:39], v[16:31]
	ds_read2_b64 v[36:39], v115 offset0:28 offset1:30
	s_waitcnt lgkmcnt(0)
	v_mfma_f32_32x32x16_bf16 v[0:15], v[32:35], v[36:39], v[0:15]
	ds_read_b64_tr_b16 v[32:33], v167 offset:8192
	ds_read_b64_tr_b16 v[34:35], v167 offset:12800
	ds_read_b64_tr_b16 v[36:37], v167 offset:17408
	ds_read_b64_tr_b16 v[38:39], v167 offset:22016
	s_waitcnt lgkmcnt(2)
	v_mfma_f32_32x32x16_bf16 v[0:15], v[32:35], v[76:79], v[0:15]
	s_waitcnt lgkmcnt(0)
	v_mfma_f32_32x32x16_bf16 v[0:15], v[36:39], v[80:83], v[0:15]
	v_mfma_f32_32x32x16_bf16 v[16:31], v[32:35], v[68:71], v[16:31]
	ds_read_b64_tr_b16 v[32:33], v167 offset:26624
	ds_read_b64_tr_b16 v[34:35], v167 offset:31232
	s_waitcnt lgkmcnt(0)
	v_mfma_f32_32x32x16_bf16 v[0:15], v[32:35], v[84:87], v[0:15]
	ds_read_b64_tr_b16 v[32:33], v167 offset:35840
	ds_read_b64_tr_b16 v[34:35], v167 offset:40448
	v_mfma_f32_32x32x16_bf16 v[16:31], v[36:39], v[64:67], v[16:31]
	s_waitcnt lgkmcnt(0)
	v_mfma_f32_32x32x16_bf16 v[0:15], v[32:35], v[72:75], v[0:15]
	s_nop 9
	v_mul_f32_e32 v32, v17, v17
	v_fmac_f32_e32 v32, v16, v16
	v_fmac_f32_e32 v32, v18, v18
	v_fmac_f32_e32 v32, v19, v19
	v_fmac_f32_e32 v32, v20, v20
	v_fmac_f32_e32 v32, v21, v21
	v_fmac_f32_e32 v32, v22, v22
	v_mul_f32_e32 v33, v1, v1
	v_fmac_f32_e32 v33, v0, v0
	v_fmac_f32_e32 v33, v2, v2
	v_fmac_f32_e32 v33, v3, v3
	v_fmac_f32_e32 v33, v4, v4
	v_fmac_f32_e32 v33, v5, v5
	v_fmac_f32_e32 v33, v6, v6
	v_fmac_f32_e32 v32, v23, v23
	v_fmac_f32_e32 v33, v7, v7
	v_fmac_f32_e32 v32, v24, v24
	v_fmac_f32_e32 v33, v8, v8
	v_fmac_f32_e32 v32, v25, v25
	v_fmac_f32_e32 v33, v9, v9
	v_fmac_f32_e32 v32, v26, v26
	v_fmac_f32_e32 v33, v10, v10
	v_fmac_f32_e32 v32, v27, v27
	v_fmac_f32_e32 v33, v11, v11
	v_fmac_f32_e32 v32, v28, v28
	v_fmac_f32_e32 v33, v12, v12
	v_fmac_f32_e32 v32, v29, v29
	v_fmac_f32_e32 v33, v13, v13
	v_fmac_f32_e32 v32, v30, v30
	v_fmac_f32_e32 v33, v14, v14
	v_fmac_f32_e32 v32, v31, v31
	v_fmac_f32_e32 v33, v15, v15
	ds_bpermute_b32 v34, v148, v32
	ds_bpermute_b32 v35, v148, v33
	s_mov_b64 s[0:1], exec
	v_readlane_b32 s24, v245, 44
	v_readlane_b32 s25, v245, 45
	s_and_b64 s[24:25], s[0:1], s[24:25]
	s_mov_b64 exec, s[24:25]
	s_cbranch_execz .LBB0_130
	s_waitcnt lgkmcnt(0)
	v_add_f32_e32 v33, v33, v35
	v_add_f32_e32 v32, v32, v34
	ds_write2_b32 v168, v32, v33 offset1:32
	s_branch .LBB0_130

.LBB0_150:
	s_ashr_i32 s0, s16, 9
	s_ashr_i32 s1, s0, 31
	s_lshl_b64 s[0:1], s[0:1], 13
	s_and_b32 s18, s5, 0x1fc0
	s_or_b32 s0, s0, s18
	v_lshl_add_u64 v[0:1], s[0:1], 0, v[18:19]
	v_mov_b64_e32 v[2:3], s[2:3]
	s_bfe_u32 s17, s16, 0x20007
	v_mad_u64_u32 v[4:5], s[18:19], v0, s64, v[2:3]
	v_mad_i32_i24 v5, v1, s64, v5
	s_lshl_b32 s18, s17, 8
	s_mov_b32 s19, s4
	v_lshl_add_u64 v[0:1], v[4:5], 0, s[18:19]
	v_lshl_add_u64 v[4:5], s[0:1], 0, v[20:21]
	v_mad_u64_u32 v[2:3], s[24:25], v4, s64, v[2:3]
	v_mad_i32_i24 v3, v5, s64, v3
	v_lshl_add_u64 v[2:3], v[2:3], 0, s[18:19]
	v_lshl_add_u64 v[0:1], v[0:1], 0, v[192:193]
	v_lshl_add_u64 v[4:5], v[2:3], 0, v[192:193]
	global_load_dwordx4 v[64:67], v[0:1], off offset:1024
	s_nop 0
	global_load_dwordx4 v[68:71], v[4:5], off offset:1024
	s_lshl_b32 s24, s17, 7
	s_and_saveexec_b64 s[18:19], s[36:37]
	s_cbranch_execz .LBB0_152
	v_lshl_add_u64 v[0:1], s[0:1], 0, v[22:23]
	v_mov_b64_e32 v[2:3], s[2:3]
	v_mad_u64_u32 v[2:3], s[26:27], v0, s64, v[2:3]
	v_mov_b32_e32 v0, v3
	v_mad_u64_u32 v[0:1], s[26:27], v1, s64, v[0:1]
	v_mov_b32_e32 v3, v0
	v_mov_b32_e32 v39, v193
	v_lshl_add_u64 v[0:1], v[2:3], 0, v[38:39]
	v_add_co_u32_e32 v0, vcc, 0x1000, v0
	s_nop 1
	v_addc_co_u32_e32 v1, vcc, 0, v1, vcc
	global_load_dwordx4 v[72:75], v[0:1], off offset:2048
.LBB0_152:
	s_or_b64 exec, exec, s[18:19]
	v_lshl_add_u64 v[0:1], s[0:1], 0, v[24:25]
	v_mov_b64_e32 v[4:5], s[2:3]
	v_mad_u64_u32 v[2:3], s[18:19], v0, s64, v[4:5]
	v_mov_b32_e32 v0, v3
	v_mad_u64_u32 v[0:1], s[18:19], v1, s64, v[0:1]
	v_mov_b32_e32 v3, v0
	s_lshl_b32 s18, s17, 9
	s_mov_b32 s19, s4
	v_lshl_add_u64 v[0:1], v[2:3], 0, s[18:19]
	v_mov_b32_e32 v41, v193
	v_lshl_add_u64 v[0:1], v[0:1], 0, v[40:41]
	global_load_dwordx4 v[76:79], v[0:1], off offset:2048
	s_mov_b32 s25, 0x7f800000
	v_lshl_add_u64 v[0:1], s[0:1], 0, v[26:27]
	v_mad_u64_u32 v[2:3], s[26:27], v0, s64, v[4:5]
	v_mov_b32_e32 v0, v3
	v_mad_u64_u32 v[0:1], s[26:27], v1, s64, v[0:1]
	v_mov_b32_e32 v3, v0
	v_lshl_add_u64 v[0:1], v[2:3], 0, s[18:19]
	v_lshl_add_u64 v[0:1], v[0:1], 0, v[40:41]
	global_load_dwordx4 v[80:83], v[0:1], off offset:2048
	v_lshl_add_u64 v[0:1], s[0:1], 0, v[28:29]
	v_mad_u64_u32 v[2:3], s[26:27], v0, s64, v[4:5]
	v_mov_b32_e32 v0, v3
	v_mad_u64_u32 v[0:1], s[26:27], v1, s64, v[0:1]
	v_mov_b32_e32 v3, v0
	v_lshl_add_u64 v[0:1], v[2:3], 0, s[18:19]
	v_lshl_add_u64 v[0:1], v[0:1], 0, v[40:41]
	global_load_dwordx4 v[84:87], v[0:1], off offset:2048
	v_lshl_add_u64 v[0:1], s[0:1], 0, v[30:31]
	v_mad_u64_u32 v[2:3], s[0:1], v0, s64, v[4:5]
	v_mov_b32_e32 v0, v3
	v_mad_u64_u32 v[0:1], s[0:1], v1, s64, v[0:1]
	v_mov_b32_e32 v3, v0
	v_lshl_add_u64 v[0:1], v[2:3], 0, s[18:19]
	v_lshl_add_u64 v[0:1], v[0:1], 0, v[40:41]
	global_load_dwordx4 v[88:91], v[0:1], off offset:2048
	v_readfirstlane_b32 s0, v16
	s_ashr_i32 s17, s0, 3
	s_lshr_b32 s0, s0, 1
	s_and_b32 s18, s0, 0x60
	v_or_b32_e32 v4, s24, v44
	v_or_b32_e32 v39, s18, v4
	v_lshlrev_b32_e32 v4, 5, v39
	v_mov_b32_e32 v5, v193
	v_lshl_add_u64 v[4:5], v[32:33], 0, v[4:5]
	v_lshlrev_b32_e32 v39, 2, v39
	s_andn2_b32 s17, s17, 31
	s_mov_b32 s19, 0xbfb8aa3b
	s_mov_b32 s24, 0x3f317217
	global_load_dwordx4 v[4:7], v[4:5], off
	global_load_dword v39, v39, s[6:7]
	s_waitcnt vmcnt(0)
	ds_write_b128 v17, v[64:67]
	ds_write_b128 v48, v[68:71]
	ds_write_b128 v50, v[76:79] offset:8192
	ds_write_b128 v51, v[80:83] offset:8192
	ds_write_b128 v52, v[84:87] offset:8192
	ds_write_b128 v53, v[88:91] offset:8192
	v_cmp_gt_u32_e32 vcc, 0x80, v195
	s_and_saveexec_b64 s[100:101], vcc
	ds_write_b128 v49, v[72:75]
	s_or_b64 exec, exec, s[100:101]
	s_waitcnt lgkmcnt(0)
	s_barrier
	v_or_b32_e32 v0, s17, v44
	v_lshl_add_u32 v0, v0, 5, v46
	ds_read_b128 v[0:3], v0
	s_waitcnt vmcnt(1) lgkmcnt(0)
	v_mfma_f32_32x32x16_bf16 v[0:15], v[0:3], v[4:7], 0
	s_waitcnt vmcnt(0)
	s_nop 10
	v_add_f32_e32 v0, v39, v0
	v_min_f32_e32 v41, 0, v0
	v_mul_f32_e64 v0, |v0|, s19
	v_exp_f32_e32 v0, v0
	v_add_f32_e32 v1, v39, v1
	v_add_f32_e32 v0, 1.0, v0
	v_cmp_gt_f32_e32 vcc, s83, v0
	s_nop 1
	v_cndmask_b32_e64 v42, 0, 32, vcc
	v_ldexp_f32 v0, v0, v42
	v_log_f32_e32 v0, v0
	s_nop 0
	v_mul_f32_e32 v42, 0x3f317217, v0
	v_fma_f32 v42, v0, s24, -v42
	v_fmac_f32_e32 v42, 0x3377d1cf, v0
	v_fmac_f32_e32 v42, 0x3f317217, v0
	v_cmp_lt_f32_e64 s[0:1], |v0|, s25
	s_nop 1
	v_cndmask_b32_e64 v0, v0, v42, s[0:1]
	v_cndmask_b32_e32 v42, 0, v211, vcc
	v_sub_f32_e32 v0, v0, v42
	v_min_f32_e32 v42, 0, v1
	v_mul_f32_e64 v1, |v1|, s19
	v_exp_f32_e32 v1, v1
	s_lshl_b32 s0, s17, 9
	s_lshl_b32 s1, s18, 2
	v_sub_f32_e32 v0, v41, v0
	v_add_f32_e32 v1, 1.0, v1
	v_cmp_gt_f32_e32 vcc, s83, v1
	s_or_b32 s0, s0, s1
	v_mul_f32_e32 v41, 0x3d800000, v0
	v_cndmask_b32_e64 v43, 0, 32, vcc
	v_ldexp_f32 v1, v1, v43
	v_log_f32_e32 v1, v1
	v_add_u32_e32 v0, s0, v47
	s_ashr_i32 s17, s16, 31
	v_mul_f32_e32 v43, 0x3f317217, v1
	v_fma_f32 v43, v1, s24, -v43
	v_fmac_f32_e32 v43, 0x3377d1cf, v1
	v_fmac_f32_e32 v43, 0x3f317217, v1
	v_cmp_lt_f32_e64 s[0:1], |v1|, s25
	s_nop 1
	v_cndmask_b32_e64 v1, v1, v43, s[0:1]
	v_cndmask_b32_e32 v43, 0, v211, vcc
	v_sub_f32_e32 v1, v1, v43
	v_sub_f32_e32 v1, v42, v1
	v_mul_f32_e32 v1, 0x3d800000, v1
	ds_write2st64_b32 v0, v41, v1 offset0:176 offset1:178
	v_add_f32_e32 v1, v39, v2
	v_min_f32_e32 v2, 0, v1
	v_mul_f32_e64 v1, |v1|, s19
	v_exp_f32_e32 v1, v1
	s_nop 0
	v_add_f32_e32 v1, 1.0, v1
	v_cmp_gt_f32_e32 vcc, s83, v1
	s_nop 1
	v_cndmask_b32_e64 v41, 0, 32, vcc
	v_ldexp_f32 v1, v1, v41
	v_log_f32_e32 v1, v1
	s_nop 0
	v_mul_f32_e32 v41, 0x3f317217, v1
	v_fma_f32 v41, v1, s24, -v41
	v_fmac_f32_e32 v41, 0x3377d1cf, v1
	v_fmac_f32_e32 v41, 0x3f317217, v1
	v_cmp_lt_f32_e64 s[0:1], |v1|, s25
	s_nop 1
	v_cndmask_b32_e64 v1, v1, v41, s[0:1]
	v_cndmask_b32_e32 v41, 0, v211, vcc
	v_sub_f32_e32 v1, v1, v41
	v_sub_f32_e32 v1, v2, v1
	v_add_f32_e32 v2, v39, v3
	v_min_f32_e32 v3, 0, v2
	v_mul_f32_e64 v2, |v2|, s19
	v_exp_f32_e32 v2, v2
	v_mul_f32_e32 v1, 0x3d800000, v1
	v_add_f32_e32 v2, 1.0, v2
	v_cmp_gt_f32_e32 vcc, s83, v2
	s_nop 1
	v_cndmask_b32_e64 v41, 0, 32, vcc
	v_ldexp_f32 v2, v2, v41
	v_log_f32_e32 v2, v2
	s_nop 0
	v_mul_f32_e32 v41, 0x3f317217, v2
	v_fma_f32 v41, v2, s24, -v41
	v_fmac_f32_e32 v41, 0x3377d1cf, v2
	v_fmac_f32_e32 v41, 0x3f317217, v2
	v_cmp_lt_f32_e64 s[0:1], |v2|, s25
	s_nop 1
	v_cndmask_b32_e64 v2, v2, v41, s[0:1]
	v_cndmask_b32_e32 v41, 0, v211, vcc
	v_sub_f32_e32 v2, v2, v41
	v_sub_f32_e32 v2, v3, v2
	v_mul_f32_e32 v2, 0x3d800000, v2
	ds_write2st64_b32 v0, v1, v2 offset0:180 offset1:182
	v_add_f32_e32 v1, v39, v4
	v_min_f32_e32 v2, 0, v1
	v_mul_f32_e64 v1, |v1|, s19
	v_exp_f32_e32 v1, v1
	s_nop 0
	v_add_f32_e32 v1, 1.0, v1
	v_cmp_gt_f32_e32 vcc, s83, v1
	s_nop 1
	v_cndmask_b32_e64 v3, 0, 32, vcc
	v_ldexp_f32 v1, v1, v3
	v_log_f32_e32 v1, v1
	s_nop 0
	v_mul_f32_e32 v3, 0x3f317217, v1
	v_fma_f32 v3, v1, s24, -v3
	v_fmac_f32_e32 v3, 0x3377d1cf, v1
	v_fmac_f32_e32 v3, 0x3f317217, v1
	v_cmp_lt_f32_e64 s[0:1], |v1|, s25
	s_nop 1
	v_cndmask_b32_e64 v1, v1, v3, s[0:1]
	v_cndmask_b32_e32 v3, 0, v211, vcc
	v_sub_f32_e32 v1, v1, v3
	v_sub_f32_e32 v1, v2, v1
	v_add_f32_e32 v2, v39, v5
	v_min_f32_e32 v3, 0, v2
	v_mul_f32_e64 v2, |v2|, s19
	v_exp_f32_e32 v2, v2
	v_mul_f32_e32 v1, 0x3d800000, v1
	v_add_f32_e32 v2, 1.0, v2
	v_cmp_gt_f32_e32 vcc, s83, v2
	s_nop 1
	v_cndmask_b32_e64 v4, 0, 32, vcc
	v_ldexp_f32 v2, v2, v4
	v_log_f32_e32 v2, v2
	s_nop 0
	v_mul_f32_e32 v4, 0x3f317217, v2
	v_fma_f32 v4, v2, s24, -v4
	v_fmac_f32_e32 v4, 0x3377d1cf, v2
	v_fmac_f32_e32 v4, 0x3f317217, v2
	v_cmp_lt_f32_e64 s[0:1], |v2|, s25
	s_nop 1
	v_cndmask_b32_e64 v2, v2, v4, s[0:1]
	v_cndmask_b32_e32 v4, 0, v211, vcc
	v_sub_f32_e32 v2, v2, v4
	v_sub_f32_e32 v2, v3, v2
	v_mul_f32_e32 v2, 0x3d800000, v2
	ds_write2st64_b32 v0, v1, v2 offset0:192 offset1:194
	v_add_f32_e32 v1, v39, v6
	v_min_f32_e32 v2, 0, v1
	v_mul_f32_e64 v1, |v1|, s19
	v_exp_f32_e32 v1, v1
	s_nop 0
	v_add_f32_e32 v1, 1.0, v1
	v_cmp_gt_f32_e32 vcc, s83, v1
	s_nop 1
	v_cndmask_b32_e64 v3, 0, 32, vcc
	v_ldexp_f32 v1, v1, v3
	v_log_f32_e32 v1, v1
	s_nop 0
	v_mul_f32_e32 v3, 0x3f317217, v1
	v_fma_f32 v3, v1, s24, -v3
	v_fmac_f32_e32 v3, 0x3377d1cf, v1
	v_fmac_f32_e32 v3, 0x3f317217, v1
	v_cmp_lt_f32_e64 s[0:1], |v1|, s25
	s_nop 1
	v_cndmask_b32_e64 v1, v1, v3, s[0:1]
	v_cndmask_b32_e32 v3, 0, v211, vcc
	v_sub_f32_e32 v1, v1, v3
	v_sub_f32_e32 v1, v2, v1
	v_add_f32_e32 v2, v39, v7
	v_min_f32_e32 v3, 0, v2
	v_mul_f32_e64 v2, |v2|, s19
	v_exp_f32_e32 v2, v2
	v_mul_f32_e32 v1, 0x3d800000, v1
	v_add_f32_e32 v2, 1.0, v2
	v_cmp_gt_f32_e32 vcc, s83, v2
	s_nop 1
	v_cndmask_b32_e64 v4, 0, 32, vcc
	v_ldexp_f32 v2, v2, v4
	v_log_f32_e32 v2, v2
	s_nop 0
	v_mul_f32_e32 v4, 0x3f317217, v2
	v_fma_f32 v4, v2, s24, -v4
	v_fmac_f32_e32 v4, 0x3377d1cf, v2
	v_fmac_f32_e32 v4, 0x3f317217, v2
	v_cmp_lt_f32_e64 s[0:1], |v2|, s25
	s_nop 1
	v_cndmask_b32_e64 v2, v2, v4, s[0:1]
	v_cndmask_b32_e32 v4, 0, v211, vcc
	v_sub_f32_e32 v2, v2, v4
	v_sub_f32_e32 v2, v3, v2
	v_mul_f32_e32 v2, 0x3d800000, v2
	ds_write2st64_b32 v0, v1, v2 offset0:196 offset1:198
	v_add_f32_e32 v1, v39, v8
	v_min_f32_e32 v2, 0, v1
	v_mul_f32_e64 v1, |v1|, s19
	v_exp_f32_e32 v1, v1
	s_nop 0
	v_add_f32_e32 v1, 1.0, v1
	v_cmp_gt_f32_e32 vcc, s83, v1
	s_nop 1
	v_cndmask_b32_e64 v3, 0, 32, vcc
	v_ldexp_f32 v1, v1, v3
	v_log_f32_e32 v1, v1
	s_nop 0
	v_mul_f32_e32 v3, 0x3f317217, v1
	v_fma_f32 v3, v1, s24, -v3
	v_fmac_f32_e32 v3, 0x3377d1cf, v1
	v_fmac_f32_e32 v3, 0x3f317217, v1
	v_cmp_lt_f32_e64 s[0:1], |v1|, s25
	s_nop 1
	v_cndmask_b32_e64 v1, v1, v3, s[0:1]
	v_cndmask_b32_e32 v3, 0, v211, vcc
	v_sub_f32_e32 v1, v1, v3
	v_sub_f32_e32 v1, v2, v1
	v_add_f32_e32 v2, v39, v9
	v_min_f32_e32 v3, 0, v2
	v_mul_f32_e64 v2, |v2|, s19
	v_exp_f32_e32 v2, v2
	v_mul_f32_e32 v1, 0x3d800000, v1
	v_add_f32_e32 v2, 1.0, v2
	v_cmp_gt_f32_e32 vcc, s83, v2
	s_nop 1
	v_cndmask_b32_e64 v4, 0, 32, vcc
	v_ldexp_f32 v2, v2, v4
	v_log_f32_e32 v2, v2
	s_nop 0
	v_mul_f32_e32 v4, 0x3f317217, v2
	v_fma_f32 v4, v2, s24, -v4
	v_fmac_f32_e32 v4, 0x3377d1cf, v2
	v_fmac_f32_e32 v4, 0x3f317217, v2
	v_cmp_lt_f32_e64 s[0:1], |v2|, s25
	s_nop 1
	v_cndmask_b32_e64 v2, v2, v4, s[0:1]
	v_cndmask_b32_e32 v4, 0, v211, vcc
	v_sub_f32_e32 v2, v2, v4
	v_sub_f32_e32 v2, v3, v2
	v_mul_f32_e32 v2, 0x3d800000, v2
	ds_write2st64_b32 v0, v1, v2 offset0:208 offset1:210
	v_add_f32_e32 v1, v39, v10
	v_min_f32_e32 v2, 0, v1
	v_mul_f32_e64 v1, |v1|, s19
	v_exp_f32_e32 v1, v1
	s_nop 0
	v_add_f32_e32 v1, 1.0, v1
	v_cmp_gt_f32_e32 vcc, s83, v1
	s_nop 1
	v_cndmask_b32_e64 v3, 0, 32, vcc
	v_ldexp_f32 v1, v1, v3
	v_log_f32_e32 v1, v1
	s_nop 0
	v_mul_f32_e32 v3, 0x3f317217, v1
	v_fma_f32 v3, v1, s24, -v3
	v_fmac_f32_e32 v3, 0x3377d1cf, v1
	v_fmac_f32_e32 v3, 0x3f317217, v1
	v_cmp_lt_f32_e64 s[0:1], |v1|, s25
	s_nop 1
	v_cndmask_b32_e64 v1, v1, v3, s[0:1]
	v_cndmask_b32_e32 v3, 0, v211, vcc
	v_sub_f32_e32 v1, v1, v3
	v_sub_f32_e32 v1, v2, v1
	v_add_f32_e32 v2, v39, v11
	v_min_f32_e32 v3, 0, v2
	v_mul_f32_e64 v2, |v2|, s19
	v_exp_f32_e32 v2, v2
	v_mul_f32_e32 v1, 0x3d800000, v1
	v_add_f32_e32 v2, 1.0, v2
	v_cmp_gt_f32_e32 vcc, s83, v2
	s_nop 1
	v_cndmask_b32_e64 v4, 0, 32, vcc
	v_ldexp_f32 v2, v2, v4
	v_log_f32_e32 v2, v2
	s_nop 0
	v_mul_f32_e32 v4, 0x3f317217, v2
	v_fma_f32 v4, v2, s24, -v4
	v_fmac_f32_e32 v4, 0x3377d1cf, v2
	v_fmac_f32_e32 v4, 0x3f317217, v2
	v_cmp_lt_f32_e64 s[0:1], |v2|, s25
	s_nop 1
	v_cndmask_b32_e64 v2, v2, v4, s[0:1]
	v_cndmask_b32_e32 v4, 0, v211, vcc
	v_sub_f32_e32 v2, v2, v4
	v_sub_f32_e32 v2, v3, v2
	v_mul_f32_e32 v2, 0x3d800000, v2
	ds_write2st64_b32 v0, v1, v2 offset0:212 offset1:214
	v_add_f32_e32 v1, v39, v12
	v_min_f32_e32 v2, 0, v1
	v_mul_f32_e64 v1, |v1|, s19
	v_exp_f32_e32 v1, v1
	s_nop 0
	v_add_f32_e32 v1, 1.0, v1
	v_cmp_gt_f32_e32 vcc, s83, v1
	s_nop 1
	v_cndmask_b32_e64 v3, 0, 32, vcc
	v_ldexp_f32 v1, v1, v3
	v_log_f32_e32 v1, v1
	s_nop 0
	v_mul_f32_e32 v3, 0x3f317217, v1
	v_fma_f32 v3, v1, s24, -v3
	v_fmac_f32_e32 v3, 0x3377d1cf, v1
	v_fmac_f32_e32 v3, 0x3f317217, v1
	v_cmp_lt_f32_e64 s[0:1], |v1|, s25
	s_nop 1
	v_cndmask_b32_e64 v1, v1, v3, s[0:1]
	v_cndmask_b32_e32 v3, 0, v211, vcc
	v_sub_f32_e32 v1, v1, v3
	v_sub_f32_e32 v1, v2, v1
	v_add_f32_e32 v2, v39, v13
	v_min_f32_e32 v3, 0, v2
	v_mul_f32_e64 v2, |v2|, s19
	v_exp_f32_e32 v2, v2
	v_mul_f32_e32 v1, 0x3d800000, v1
	v_add_f32_e32 v2, 1.0, v2
	v_cmp_gt_f32_e32 vcc, s83, v2
	s_nop 1
	v_cndmask_b32_e64 v4, 0, 32, vcc
	v_ldexp_f32 v2, v2, v4
	v_log_f32_e32 v2, v2
	s_nop 0
	v_mul_f32_e32 v4, 0x3f317217, v2
	v_fma_f32 v4, v2, s24, -v4
	v_fmac_f32_e32 v4, 0x3377d1cf, v2
	v_fmac_f32_e32 v4, 0x3f317217, v2
	v_cmp_lt_f32_e64 s[0:1], |v2|, s25
	s_nop 1
	v_cndmask_b32_e64 v2, v2, v4, s[0:1]
	v_cndmask_b32_e32 v4, 0, v211, vcc
	v_sub_f32_e32 v2, v2, v4
	v_sub_f32_e32 v2, v3, v2
	v_mul_f32_e32 v2, 0x3d800000, v2
	ds_write2st64_b32 v0, v1, v2 offset0:224 offset1:226
	v_add_f32_e32 v1, v39, v14
	v_min_f32_e32 v2, 0, v1
	v_mul_f32_e64 v1, |v1|, s19
	v_exp_f32_e32 v1, v1
	s_nop 0
	v_add_f32_e32 v1, 1.0, v1
	v_cmp_gt_f32_e32 vcc, s83, v1
	s_nop 1
	v_cndmask_b32_e64 v3, 0, 32, vcc
	v_ldexp_f32 v1, v1, v3
	v_log_f32_e32 v1, v1
	s_nop 0
	v_mul_f32_e32 v3, 0x3f317217, v1
	v_fma_f32 v3, v1, s24, -v3
	v_fmac_f32_e32 v3, 0x3377d1cf, v1
	v_fmac_f32_e32 v3, 0x3f317217, v1
	v_cmp_lt_f32_e64 s[0:1], |v1|, s25
	s_nop 1
	v_cndmask_b32_e64 v1, v1, v3, s[0:1]
	v_cndmask_b32_e32 v3, 0, v211, vcc
	v_sub_f32_e32 v1, v1, v3
	v_sub_f32_e32 v1, v2, v1
	v_add_f32_e32 v2, v39, v15
	v_min_f32_e32 v3, 0, v2
	v_mul_f32_e64 v2, |v2|, s19
	v_exp_f32_e32 v2, v2
	v_mul_f32_e32 v1, 0x3d800000, v1
	v_add_f32_e32 v2, 1.0, v2
	v_cmp_gt_f32_e32 vcc, s83, v2
	s_nop 1
	v_cndmask_b32_e64 v4, 0, 32, vcc
	v_ldexp_f32 v2, v2, v4
	v_log_f32_e32 v2, v2
	s_nop 0
	v_mul_f32_e32 v4, 0x3f317217, v2
	v_fma_f32 v4, v2, s24, -v4
	v_fmac_f32_e32 v4, 0x3377d1cf, v2
	v_fmac_f32_e32 v4, 0x3f317217, v2
	v_cmp_lt_f32_e64 s[0:1], |v2|, s25
	s_nop 1
	v_cndmask_b32_e64 v2, v2, v4, s[0:1]
	v_cndmask_b32_e32 v4, 0, v211, vcc
	v_sub_f32_e32 v2, v2, v4
	v_sub_f32_e32 v2, v3, v2
	v_mul_f32_e32 v2, 0x3d800000, v2
	ds_write2st64_b32 v0, v1, v2 offset0:228 offset1:230
	s_waitcnt lgkmcnt(0)
	s_barrier
	ds_read2st64_b32 v[0:1], v54 offset0:176 offset1:178
	s_waitcnt lgkmcnt(0)
	v_add_f32_e32 v6, 0, v0
	v_add_f32_e32 v8, v6, v1
	ds_read2st64_b32 v[0:1], v54 offset0:180 offset1:182
	s_waitcnt lgkmcnt(0)
	v_add_f32_e32 v9, v8, v0
	v_add_f32_e32 v10, v9, v1
	ds_read2st64_b32 v[0:1], v54 offset0:184 offset1:186
	s_waitcnt lgkmcnt(0)
	v_add_f32_e32 v11, v10, v0
	v_add_f32_e32 v12, v11, v1
	ds_read2st64_b32 v[0:1], v54 offset0:188 offset1:190
	s_waitcnt lgkmcnt(0)
	v_add_f32_e32 v13, v12, v0
	v_add_f32_e32 v14, v13, v1
	ds_read2st64_b32 v[0:1], v54 offset0:192 offset1:194
	s_waitcnt lgkmcnt(0)
	v_add_f32_e32 v15, v14, v0
	v_add_f32_e32 v39, v15, v1
	ds_read2st64_b32 v[0:1], v54 offset0:196 offset1:198
	s_waitcnt lgkmcnt(0)
	v_add_f32_e32 v41, v39, v0
	v_add_f32_e32 v42, v41, v1
	ds_read2st64_b32 v[0:1], v54 offset0:200 offset1:202
	s_waitcnt lgkmcnt(0)
	v_add_f32_e32 v43, v42, v0
	v_add_f32_e32 v60, v43, v1
	ds_read2st64_b32 v[0:1], v54 offset0:204 offset1:206
	s_waitcnt lgkmcnt(0)
	v_add_f32_e32 v0, v60, v0
	v_add_f32_e32 v1, v0, v1
	ds_write_b32 v55, v1 offset:4096
	s_waitcnt lgkmcnt(0)
	s_barrier
	ds_read2st64_b32 v[2:3], v45 offset0:16 offset1:18
	s_waitcnt lgkmcnt(0)
	v_add_f32_e32 v2, 0, v2
	v_cndmask_b32_e64 v4, 0, v2, s[38:39]
	v_add_f32_e32 v5, v3, v4
	v_cndmask_b32_e64 v7, v4, v5, s[40:41]
	ds_read2st64_b32 v[4:5], v45 offset0:20 offset1:22
	s_waitcnt lgkmcnt(0)
	v_add_f32_e32 v61, v4, v7
	v_cndmask_b32_e64 v7, v7, v61, s[42:43]
	v_add_f32_e32 v61, v5, v7
	v_cndmask_b32_e64 v7, v7, v61, s[44:45]
	v_add_f32_e32 v62, v0, v7
	v_add_f32_e32 v0, v2, v3
	v_add_f32_e32 v61, v6, v7
	v_add_f32_e32 v0, v0, v4
	v_mov_b32_e32 v6, v5
	v_add_f32_e32 v8, v8, v7
	v_pk_add_f32 v[0:1], v[0:1], v[6:7]
	ds_read_u16 v4, v56
	ds_read_u16 v5, v56 offset:256
	v_sub_f32_e32 v2, v0, v61
	v_sub_f32_e32 v3, v0, v8
	v_mul_f32_e32 v2, 0x3fb8aa3b, v2
	v_mul_f32_e32 v3, 0x3fb8aa3b, v3
	v_exp_f32_e32 v2, v2
	v_exp_f32_e32 v3, v3
	v_add_f32_e32 v9, v9, v7
	v_add_f32_e32 v10, v10, v7
	s_waitcnt lgkmcnt(0)
	v_lshlrev_b32_e32 v5, 16, v5
	v_lshlrev_b32_e32 v4, 16, v4
	v_add_f32_e32 v11, v11, v7
	v_add_f32_e32 v12, v12, v7
	v_add_f32_e32 v13, v13, v7
	v_add_f32_e32 v14, v14, v7
	v_add_f32_e32 v15, v15, v7
	v_add_f32_e32 v39, v39, v7
	v_add_f32_e32 v41, v41, v7
	v_add_f32_e32 v42, v42, v7
	v_add_f32_e32 v43, v43, v7
	v_add_f32_e32 v60, v60, v7
	v_pk_mul_f32 v[2:3], v[2:3], v[4:5]
	v_sub_f32_e32 v4, v0, v9
	v_sub_f32_e32 v5, v0, v10
	ds_read_u16 v6, v56 offset:512
	ds_read_u16 v7, v56 offset:768
	v_mul_f32_e32 v4, 0x3fb8aa3b, v4
	v_mul_f32_e32 v5, 0x3fb8aa3b, v5
	v_exp_f32_e32 v4, v4
	v_exp_f32_e32 v5, v5
	s_waitcnt lgkmcnt(0)
	v_lshlrev_b32_e32 v7, 16, v7
	v_lshlrev_b32_e32 v6, 16, v6
	ds_read_u16 v8, v56 offset:1024
	ds_read_u16 v9, v56 offset:1280
	v_pk_mul_f32 v[4:5], v[4:5], v[6:7]
	v_sub_f32_e32 v6, v0, v11
	v_sub_f32_e32 v7, v0, v12
	v_mul_f32_e32 v6, 0x3fb8aa3b, v6
	v_mul_f32_e32 v7, 0x3fb8aa3b, v7
	v_exp_f32_e32 v6, v6
	v_exp_f32_e32 v7, v7
	s_waitcnt lgkmcnt(0)
	v_lshlrev_b32_e32 v9, 16, v9
	v_lshlrev_b32_e32 v8, 16, v8
	ds_read_u16 v10, v56 offset:1536
	ds_read_u16 v11, v56 offset:1792
	v_pk_mul_f32 v[6:7], v[6:7], v[8:9]
	v_sub_f32_e32 v8, v0, v13
	v_sub_f32_e32 v9, v0, v14
	v_mul_f32_e32 v8, 0x3fb8aa3b, v8
	v_mul_f32_e32 v9, 0x3fb8aa3b, v9
	v_exp_f32_e32 v8, v8
	v_exp_f32_e32 v9, v9
	s_waitcnt lgkmcnt(0)
	v_lshlrev_b32_e32 v11, 16, v11
	v_lshlrev_b32_e32 v10, 16, v10
	ds_read_u16 v12, v56 offset:2048
	ds_read_u16 v13, v56 offset:2304
	v_pk_mul_f32 v[8:9], v[8:9], v[10:11]
	v_sub_f32_e32 v10, v0, v15
	v_sub_f32_e32 v11, v0, v39
	v_mul_f32_e32 v10, 0x3fb8aa3b, v10
	v_mul_f32_e32 v11, 0x3fb8aa3b, v11
	v_exp_f32_e32 v10, v10
	v_exp_f32_e32 v11, v11
	s_waitcnt lgkmcnt(0)
	v_lshlrev_b32_e32 v13, 16, v13
	v_lshlrev_b32_e32 v12, 16, v12
	ds_read_u16 v14, v56 offset:2560
	ds_read_u16 v15, v56 offset:2816
	v_pk_mul_f32 v[10:11], v[10:11], v[12:13]
	v_sub_f32_e32 v12, v0, v41
	v_sub_f32_e32 v13, v0, v42
	v_mul_f32_e32 v12, 0x3fb8aa3b, v12
	v_mul_f32_e32 v13, 0x3fb8aa3b, v13
	v_exp_f32_e32 v12, v12
	v_exp_f32_e32 v13, v13
	s_waitcnt lgkmcnt(0)
	v_lshlrev_b32_e32 v15, 16, v15
	v_lshlrev_b32_e32 v14, 16, v14
	ds_read_u16 v39, v56 offset:3072
	ds_read_u16 v41, v56 offset:3328
	v_pk_mul_f32 v[12:13], v[12:13], v[14:15]
	v_sub_f32_e32 v14, v0, v43
	v_sub_f32_e32 v15, v0, v60
	v_mul_f32_e32 v14, 0x3fb8aa3b, v14
	v_mul_f32_e32 v15, 0x3fb8aa3b, v15
	v_exp_f32_e32 v14, v14
	v_exp_f32_e32 v15, v15
	s_waitcnt lgkmcnt(1)
	v_lshlrev_b32_e32 v42, 16, v39
	v_sub_f32_e32 v39, v0, v62
	v_sub_f32_e32 v1, v0, v1
	s_waitcnt lgkmcnt(0)
	v_lshlrev_b32_e32 v43, 16, v41
	v_mul_f32_e32 v39, 0x3fb8aa3b, v39
	v_mul_f32_e32 v1, 0x3fb8aa3b, v1
	v_pk_mul_f32 v[14:15], v[14:15], v[42:43]
	v_exp_f32_e32 v42, v39
	v_exp_f32_e32 v43, v1
	ds_read_u16 v1, v56 offset:3584
	ds_read_u16 v39, v56 offset:3840
	v_cvt_pk_bf16_f32 v2, v2, v3
	v_cvt_pk_bf16_f32 v3, v4, v5
	v_cvt_pk_bf16_f32 v4, v6, v7
	s_waitcnt lgkmcnt(1)
	v_lshlrev_b32_e32 v60, 16, v1
	s_waitcnt lgkmcnt(0)
	v_lshlrev_b32_e32 v61, 16, v39
	v_pk_mul_f32 v[42:43], v[42:43], v[60:61]
	v_cvt_pk_bf16_f32 v5, v8, v9
	v_cvt_pk_bf16_f32 v6, v10, v11
	v_cvt_pk_bf16_f32 v7, v12, v13
	v_cvt_pk_bf16_f32 v8, v14, v15
	v_cvt_pk_bf16_f32 v9, v42, v43
	ds_write_b128 v57, v[2:5] offset:45056
	ds_write_b128 v57, v[6:9] offset:45072
	s_and_saveexec_b64 s[0:1], s[46:47]
	s_cbranch_execz .LBB0_149
	v_mul_f32_e32 v0, 0x3fb8aa3b, v0
	v_exp_f32_e32 v2, v0
	s_lshl_b64 s[18:19], s[16:17], 9
	v_lshl_add_u64 v[0:1], v[34:35], 0, s[18:19]
	flat_store_dword v[0:1], v2
	s_branch .LBB0_149

.Lat_noqk1_4:
	s_mov_b32 s5, 1
	s_mov_b32 s12, 18432
	s_mov_b32 s13, 0
	s_mov_b32 s11, 0
	v_add_u32_e32 v215, s11, v201
	ds_read_b64_tr_b16 v[224:225], v215 offset:27648
	ds_read_b64_tr_b16 v[226:227], v215 offset:30208
	ds_read_b64_tr_b16 v[228:229], v215 offset:27712
	ds_read_b64_tr_b16 v[230:231], v215 offset:30272
	ds_read_b64_tr_b16 v[232:233], v215 offset:27776
	ds_read_b64_tr_b16 v[234:235], v215 offset:30336
	ds_read_b64_tr_b16 v[236:237], v215 offset:27840
	ds_read_b64_tr_b16 v[238:239], v215 offset:30400
	s_waitcnt lgkmcnt(8)
	s_barrier

.Lat_noload_6:
.Lat_nostage_5:
	s_add_i32 s16, s81, 1
	s_cmp_gt_i32 s5, s16
	s_cbranch_scc1 .Lat_xdone_7
	s_add_i32 s8, s5, -1
	s_and_b32 s8, s8, 3
	s_mul_i32 s11, s8, 20480
	v_add_u32_e32 v189, s12, v200
	s_cmp_gt_i32 s5, s81
	s_cbranch_scc1 .Lat_pvonly_8
	v_add_u32_e32 v215, s11, v201
	ds_read_b64_tr_b16 v[240:241], v215 offset:32768
	ds_read_b64_tr_b16 v[242:243], v215 offset:35328
	ds_read_b64_tr_b16 v[130:131], v215 offset:32832
	ds_read_b64_tr_b16 v[132:133], v215 offset:35392
	ds_read_b64_tr_b16 v[134:135], v215 offset:32896
	ds_read_b64_tr_b16 v[136:137], v215 offset:35456
	ds_read_b64_tr_b16 v[184:185], v215 offset:32960
	ds_read_b64_tr_b16 v[186:187], v215 offset:35520
	s_waitcnt lgkmcnt(14)
	v_mfma_f32_32x32x16_bf16 v[0:15], v[224:227], v[114:117], v[0:15]
	v_exp_f32_e32 v82, v82
	v_exp_f32_e32 v83, v83
	v_mov_b32_e32 v180, 0
	s_waitcnt lgkmcnt(12)
	v_mfma_f32_32x32x16_bf16 v[16:31], v[228:231], v[114:117], v[16:31]
	v_exp_f32_e32 v84, v84
	v_exp_f32_e32 v85, v85
	v_add_f32_e32 v180, v180, v82
	v_add_f32_e32 v180, v180, v83
	s_waitcnt lgkmcnt(10)
	v_mfma_f32_32x32x16_bf16 v[32:47], v[232:235], v[114:117], v[32:47]
	v_exp_f32_e32 v86, v86
	v_exp_f32_e32 v87, v87
	v_add_f32_e32 v180, v180, v84
	v_add_f32_e32 v180, v180, v85
	s_waitcnt lgkmcnt(8)
	v_mfma_f32_32x32x16_bf16 v[48:63], v[236:239], v[114:117], v[48:63]
	v_exp_f32_e32 v88, v88
	v_exp_f32_e32 v89, v89
	v_add_f32_e32 v180, v180, v86
	v_add_f32_e32 v180, v180, v87
	ds_read_b64_tr_b16 v[224:225], v215 offset:37888
	ds_read_b64_tr_b16 v[226:227], v215 offset:40448
	ds_read_b64_tr_b16 v[228:229], v215 offset:37952
	ds_read_b64_tr_b16 v[230:231], v215 offset:40512
	ds_read_b64_tr_b16 v[232:233], v215 offset:38016
	ds_read_b64_tr_b16 v[234:235], v215 offset:40576
	ds_read_b64_tr_b16 v[236:237], v215 offset:38080
	ds_read_b64_tr_b16 v[238:239], v215 offset:40640
	s_waitcnt lgkmcnt(14)
	v_mfma_f32_32x32x16_bf16 v[0:15], v[240:243], v[118:121], v[0:15]
	v_exp_f32_e32 v90, v90
	v_exp_f32_e32 v91, v91
	v_add_f32_e32 v180, v180, v88
	v_add_f32_e32 v180, v180, v89
	v_cvt_pk_bf16_f32 v114, v82, v83
	s_waitcnt lgkmcnt(12)
	v_mfma_f32_32x32x16_bf16 v[16:31], v[130:133], v[118:121], v[16:31]
	v_exp_f32_e32 v92, v92
	v_exp_f32_e32 v93, v93
	v_add_f32_e32 v180, v180, v90
	v_add_f32_e32 v180, v180, v91
	v_cvt_pk_bf16_f32 v115, v84, v85
	s_waitcnt lgkmcnt(10)
	v_mfma_f32_32x32x16_bf16 v[32:47], v[134:137], v[118:121], v[32:47]
	v_exp_f32_e32 v94, v94
	v_exp_f32_e32 v95, v95
	v_add_f32_e32 v180, v180, v92
	v_add_f32_e32 v180, v180, v93
	v_cvt_pk_bf16_f32 v116, v86, v87
	s_waitcnt lgkmcnt(8)
	v_mfma_f32_32x32x16_bf16 v[48:63], v[184:187], v[118:121], v[48:63]
	v_exp_f32_e32 v96, v96
	v_exp_f32_e32 v97, v97
	v_add_f32_e32 v180, v180, v94
	v_add_f32_e32 v180, v180, v95
	v_cvt_pk_bf16_f32 v117, v88, v89
	ds_read_b64_tr_b16 v[240:241], v215 offset:43008
	ds_read_b64_tr_b16 v[242:243], v215 offset:45568
	ds_read_b64_tr_b16 v[130:131], v215 offset:43072
	ds_read_b64_tr_b16 v[132:133], v215 offset:45632
	ds_read_b64_tr_b16 v[134:135], v215 offset:43136
	ds_read_b64_tr_b16 v[136:137], v215 offset:45696
	ds_read_b64_tr_b16 v[184:185], v215 offset:43200
	ds_read_b64_tr_b16 v[186:187], v215 offset:45760
	s_waitcnt lgkmcnt(14)
	v_mfma_f32_32x32x16_bf16 v[0:15], v[224:227], v[122:125], v[0:15]
	v_exp_f32_e32 v98, v98
	v_exp_f32_e32 v99, v99
	v_add_f32_e32 v180, v180, v96
	v_add_f32_e32 v180, v180, v97
	v_cvt_pk_bf16_f32 v118, v90, v91
	s_waitcnt lgkmcnt(12)
	v_mfma_f32_32x32x16_bf16 v[16:31], v[228:231], v[122:125], v[16:31]
	v_exp_f32_e32 v100, v100
	v_exp_f32_e32 v101, v101
	v_add_f32_e32 v180, v180, v98
	v_add_f32_e32 v180, v180, v99
	v_cvt_pk_bf16_f32 v119, v92, v93
	s_waitcnt lgkmcnt(10)
	v_mfma_f32_32x32x16_bf16 v[32:47], v[232:235], v[122:125], v[32:47]
	v_exp_f32_e32 v102, v102
	v_exp_f32_e32 v103, v103
	v_add_f32_e32 v180, v180, v100
	v_add_f32_e32 v180, v180, v101
	v_cvt_pk_bf16_f32 v120, v94, v95
	s_waitcnt lgkmcnt(8)
	v_mfma_f32_32x32x16_bf16 v[48:63], v[236:239], v[122:125], v[48:63]
	v_exp_f32_e32 v104, v104
	v_exp_f32_e32 v105, v105
	v_add_f32_e32 v180, v180, v102
	v_add_f32_e32 v180, v180, v103
	v_cvt_pk_bf16_f32 v121, v96, v97
	ds_read_b128 v[224:227], v189
	ds_read_b128 v[228:231], v189 offset:4608
	ds_read_b128 v[232:235], v189 offset:32
	ds_read_b128 v[236:239], v189 offset:4640
	s_waitcnt lgkmcnt(10)
	v_mfma_f32_32x32x16_bf16 v[0:15], v[240:243], v[126:129], v[0:15]
	v_exp_f32_e32 v106, v106
	v_exp_f32_e32 v107, v107
	v_add_f32_e32 v180, v180, v104
	v_add_f32_e32 v180, v180, v105
	v_cvt_pk_bf16_f32 v122, v98, v99
	s_waitcnt lgkmcnt(8)
	v_mfma_f32_32x32x16_bf16 v[16:31], v[130:133], v[126:129], v[16:31]
	v_exp_f32_e32 v108, v108
	v_exp_f32_e32 v109, v109
	v_add_f32_e32 v180, v180, v106
	v_add_f32_e32 v180, v180, v107
	v_cvt_pk_bf16_f32 v123, v100, v101
	s_waitcnt lgkmcnt(6)
	v_mfma_f32_32x32x16_bf16 v[32:47], v[134:137], v[126:129], v[32:47]
	v_exp_f32_e32 v110, v110
	v_exp_f32_e32 v111, v111
	v_add_f32_e32 v180, v180, v108
	v_add_f32_e32 v180, v180, v109
	v_cvt_pk_bf16_f32 v124, v102, v103
	s_waitcnt lgkmcnt(4)
	v_mfma_f32_32x32x16_bf16 v[48:63], v[184:187], v[126:129], v[48:63]
	v_exp_f32_e32 v112, v112
	v_exp_f32_e32 v113, v113
	v_add_f32_e32 v180, v180, v110
	v_add_f32_e32 v180, v180, v111
	v_cvt_pk_bf16_f32 v125, v104, v105
	s_nop 0
	v_add_f32_e32 v180, v180, v112
	v_add_f32_e32 v180, v180, v113
	v_cvt_pk_bf16_f32 v126, v106, v107
	v_cvt_pk_bf16_f32 v127, v108, v109
	v_cvt_pk_bf16_f32 v128, v110, v111
	v_cvt_pk_bf16_f32 v129, v112, v113
	v_cmp_ngt_f32_e32 vcc, s23, v180
	s_cbranch_vccz .Lat_norescale_9
	ds_bpermute_b32 v182, v214, v180
	s_waitcnt lgkmcnt(0)
	v_add_f32_e32 v182, v180, v182
	v_min_f32_e32 v182, 0x7f61b1e6, v182
	v_log_f32_e32 v182, v182
	s_nop 0
	v_floor_f32_e32 v182, v182
	v_max_f32_e32 v182, 0, v182
	v_exp_f32_e64 v183, -v182
	v_add_f32_e32 v80, v80, v182
	v_mul_f32_e32 v81, v81, v183
	v_mul_f32_e32 v180, v180, v183
	v_xor_b32_e32 v64, 0x80000000, v80
	v_mov_b32_e32 v65, v64
	v_mov_b32_e32 v66, v64
	v_mov_b32_e32 v67, v64
	v_mov_b32_e32 v68, v64
	v_mov_b32_e32 v69, v64
	v_mov_b32_e32 v70, v64
	v_mov_b32_e32 v71, v64
	v_mov_b32_e32 v72, v64
	v_mov_b32_e32 v73, v64
	v_mov_b32_e32 v74, v64
	v_mov_b32_e32 v75, v64
	v_mov_b32_e32 v76, v64
	v_mov_b32_e32 v77, v64
	v_mov_b32_e32 v78, v64
	v_mov_b32_e32 v79, v64
	v_mul_f32_e32 v82, v82, v183
	v_mul_f32_e32 v83, v83, v183
	v_mul_f32_e32 v84, v84, v183
	v_mul_f32_e32 v85, v85, v183
	v_mul_f32_e32 v86, v86, v183
	v_mul_f32_e32 v87, v87, v183
	v_mul_f32_e32 v88, v88, v183
	v_mul_f32_e32 v89, v89, v183
	v_mul_f32_e32 v90, v90, v183
	v_mul_f32_e32 v91, v91, v183
	v_mul_f32_e32 v92, v92, v183
	v_mul_f32_e32 v93, v93, v183
	v_mul_f32_e32 v94, v94, v183
	v_mul_f32_e32 v95, v95, v183
	v_mul_f32_e32 v96, v96, v183
	v_mul_f32_e32 v97, v97, v183
	v_mul_f32_e32 v98, v98, v183
	v_mul_f32_e32 v99, v99, v183
	v_mul_f32_e32 v100, v100, v183
	v_mul_f32_e32 v101, v101, v183
	v_mul_f32_e32 v102, v102, v183
	v_mul_f32_e32 v103, v103, v183
	v_mul_f32_e32 v104, v104, v183
	v_mul_f32_e32 v105, v105, v183
	v_mul_f32_e32 v106, v106, v183
	v_mul_f32_e32 v107, v107, v183
	v_mul_f32_e32 v108, v108, v183
	v_mul_f32_e32 v109, v109, v183
	v_mul_f32_e32 v110, v110, v183
	v_mul_f32_e32 v111, v111, v183
	v_mul_f32_e32 v112, v112, v183
	v_mul_f32_e32 v113, v113, v183
	v_mul_f32_e32 v0, v0, v183
	v_mul_f32_e32 v1, v1, v183
	v_mul_f32_e32 v2, v2, v183
	v_mul_f32_e32 v3, v3, v183
	v_mul_f32_e32 v4, v4, v183
	v_mul_f32_e32 v5, v5, v183
	v_mul_f32_e32 v6, v6, v183
	v_mul_f32_e32 v7, v7, v183
	v_mul_f32_e32 v8, v8, v183
	v_mul_f32_e32 v9, v9, v183
	v_mul_f32_e32 v10, v10, v183
	v_mul_f32_e32 v11, v11, v183
	v_mul_f32_e32 v12, v12, v183
	v_mul_f32_e32 v13, v13, v183
	v_mul_f32_e32 v14, v14, v183
	v_mul_f32_e32 v15, v15, v183
	v_mul_f32_e32 v16, v16, v183
	v_mul_f32_e32 v17, v17, v183
	v_mul_f32_e32 v18, v18, v183
	v_mul_f32_e32 v19, v19, v183
	v_mul_f32_e32 v20, v20, v183
	v_mul_f32_e32 v21, v21, v183
	v_mul_f32_e32 v22, v22, v183
	v_mul_f32_e32 v23, v23, v183
	v_mul_f32_e32 v24, v24, v183
	v_mul_f32_e32 v25, v25, v183
	v_mul_f32_e32 v26, v26, v183
	v_mul_f32_e32 v27, v27, v183
	v_mul_f32_e32 v28, v28, v183
	v_mul_f32_e32 v29, v29, v183
	v_mul_f32_e32 v30, v30, v183
	v_mul_f32_e32 v31, v31, v183
	v_mul_f32_e32 v32, v32, v183
	v_mul_f32_e32 v33, v33, v183
	v_mul_f32_e32 v34, v34, v183
	v_mul_f32_e32 v35, v35, v183
	v_mul_f32_e32 v36, v36, v183
	v_mul_f32_e32 v37, v37, v183
	v_mul_f32_e32 v38, v38, v183
	v_mul_f32_e32 v39, v39, v183
	v_mul_f32_e32 v40, v40, v183
	v_mul_f32_e32 v41, v41, v183
	v_mul_f32_e32 v42, v42, v183
	v_mul_f32_e32 v43, v43, v183
	v_mul_f32_e32 v44, v44, v183
	v_mul_f32_e32 v45, v45, v183
	v_mul_f32_e32 v46, v46, v183
	v_mul_f32_e32 v47, v47, v183
	v_mul_f32_e32 v48, v48, v183
	v_mul_f32_e32 v49, v49, v183
	v_mul_f32_e32 v50, v50, v183
	v_mul_f32_e32 v51, v51, v183
	v_mul_f32_e32 v52, v52, v183
	v_mul_f32_e32 v53, v53, v183
	v_mul_f32_e32 v54, v54, v183
	v_mul_f32_e32 v55, v55, v183
	v_mul_f32_e32 v56, v56, v183
	v_mul_f32_e32 v57, v57, v183
	v_mul_f32_e32 v58, v58, v183
	v_mul_f32_e32 v59, v59, v183
	v_mul_f32_e32 v60, v60, v183
	v_mul_f32_e32 v61, v61, v183
	v_mul_f32_e32 v62, v62, v183
	v_mul_f32_e32 v63, v63, v183
	v_cvt_pk_bf16_f32 v114, v82, v83
	v_cvt_pk_bf16_f32 v115, v84, v85
	v_cvt_pk_bf16_f32 v116, v86, v87
	v_cvt_pk_bf16_f32 v117, v88, v89
	v_cvt_pk_bf16_f32 v118, v90, v91
	v_cvt_pk_bf16_f32 v119, v92, v93
	v_cvt_pk_bf16_f32 v120, v94, v95
	v_cvt_pk_bf16_f32 v121, v96, v97
	v_cvt_pk_bf16_f32 v122, v98, v99
	v_cvt_pk_bf16_f32 v123, v100, v101
	v_cvt_pk_bf16_f32 v124, v102, v103
	v_cvt_pk_bf16_f32 v125, v104, v105
	v_cvt_pk_bf16_f32 v126, v106, v107
	v_cvt_pk_bf16_f32 v127, v108, v109
	v_cvt_pk_bf16_f32 v128, v110, v111
	v_cvt_pk_bf16_f32 v129, v112, v113

.Lat_pvonly_8:
	v_add_u32_e32 v215, s11, v201
	ds_read_b64_tr_b16 v[240:241], v215 offset:32768
	ds_read_b64_tr_b16 v[242:243], v215 offset:35328
	ds_read_b64_tr_b16 v[130:131], v215 offset:32832
	ds_read_b64_tr_b16 v[132:133], v215 offset:35392
	ds_read_b64_tr_b16 v[134:135], v215 offset:32896
	ds_read_b64_tr_b16 v[136:137], v215 offset:35456
	ds_read_b64_tr_b16 v[184:185], v215 offset:32960
	ds_read_b64_tr_b16 v[186:187], v215 offset:35520
	s_waitcnt lgkmcnt(14)
	v_mfma_f32_32x32x16_bf16 v[0:15], v[224:227], v[114:117], v[0:15]
	s_waitcnt lgkmcnt(12)
	v_mfma_f32_32x32x16_bf16 v[16:31], v[228:231], v[114:117], v[16:31]
	s_waitcnt lgkmcnt(10)
	v_mfma_f32_32x32x16_bf16 v[32:47], v[232:235], v[114:117], v[32:47]
	s_waitcnt lgkmcnt(8)
	v_mfma_f32_32x32x16_bf16 v[48:63], v[236:239], v[114:117], v[48:63]
	ds_read_b64_tr_b16 v[224:225], v215 offset:37888
	ds_read_b64_tr_b16 v[226:227], v215 offset:40448
	ds_read_b64_tr_b16 v[228:229], v215 offset:37952
	ds_read_b64_tr_b16 v[230:231], v215 offset:40512
	ds_read_b64_tr_b16 v[232:233], v215 offset:38016
	ds_read_b64_tr_b16 v[234:235], v215 offset:40576
	ds_read_b64_tr_b16 v[236:237], v215 offset:38080
	ds_read_b64_tr_b16 v[238:239], v215 offset:40640
	s_waitcnt lgkmcnt(14)
	v_mfma_f32_32x32x16_bf16 v[0:15], v[240:243], v[118:121], v[0:15]
	s_waitcnt lgkmcnt(12)
	v_mfma_f32_32x32x16_bf16 v[16:31], v[130:133], v[118:121], v[16:31]
	s_waitcnt lgkmcnt(10)
	v_mfma_f32_32x32x16_bf16 v[32:47], v[134:137], v[118:121], v[32:47]
	s_waitcnt lgkmcnt(8)
	v_mfma_f32_32x32x16_bf16 v[48:63], v[184:187], v[118:121], v[48:63]
	ds_read_b64_tr_b16 v[240:241], v215 offset:43008
	ds_read_b64_tr_b16 v[242:243], v215 offset:45568
	ds_read_b64_tr_b16 v[130:131], v215 offset:43072
	ds_read_b64_tr_b16 v[132:133], v215 offset:45632
	ds_read_b64_tr_b16 v[134:135], v215 offset:43136
	ds_read_b64_tr_b16 v[136:137], v215 offset:45696
	ds_read_b64_tr_b16 v[184:185], v215 offset:43200
	ds_read_b64_tr_b16 v[186:187], v215 offset:45760
	s_waitcnt lgkmcnt(14)
	v_mfma_f32_32x32x16_bf16 v[0:15], v[224:227], v[122:125], v[0:15]
	s_waitcnt lgkmcnt(12)
	v_mfma_f32_32x32x16_bf16 v[16:31], v[228:231], v[122:125], v[16:31]
	s_waitcnt lgkmcnt(10)
	v_mfma_f32_32x32x16_bf16 v[32:47], v[232:235], v[122:125], v[32:47]
	s_waitcnt lgkmcnt(8)
	v_mfma_f32_32x32x16_bf16 v[48:63], v[236:239], v[122:125], v[48:63]
	s_waitcnt lgkmcnt(6)
	v_mfma_f32_32x32x16_bf16 v[0:15], v[240:243], v[126:129], v[0:15]
	s_waitcnt lgkmcnt(4)
	v_mfma_f32_32x32x16_bf16 v[16:31], v[130:133], v[126:129], v[16:31]
	s_waitcnt lgkmcnt(2)
	v_mfma_f32_32x32x16_bf16 v[32:47], v[134:137], v[126:129], v[32:47]
	s_waitcnt lgkmcnt(0)
	v_mfma_f32_32x32x16_bf16 v[48:63], v[184:187], v[126:129], v[48:63]
.Lat_xdone_7:
	s_add_i32 s8, s5, 1
	s_cmp_gt_i32 s8, s81
	s_cbranch_scc1 .Lat_noqk_10
	ds_read_b128 v[240:243], v189 offset:64
	ds_read_b128 v[130:133], v189 offset:4672
	ds_read_b128 v[134:137], v189 offset:96
	ds_read_b128 v[184:187], v189 offset:4704
	s_waitcnt lgkmcnt(7)
	v_mfma_f32_32x32x16_bf16 v[82:97], v[224:227], v[150:153], v[64:79]
	s_waitcnt lgkmcnt(6)
	v_mfma_f32_32x32x16_bf16 v[98:113], v[228:231], v[150:153], v[64:79]
	s_waitcnt lgkmcnt(5)
	v_mfma_f32_32x32x16_bf16 v[82:97], v[232:235], v[146:149], v[82:97]
	s_waitcnt lgkmcnt(4)
	v_mfma_f32_32x32x16_bf16 v[98:113], v[236:239], v[146:149], v[98:113]
	s_waitcnt lgkmcnt(3)
	v_mfma_f32_32x32x16_bf16 v[82:97], v[240:243], v[142:145], v[82:97]
	s_waitcnt lgkmcnt(2)
	v_mfma_f32_32x32x16_bf16 v[98:113], v[130:133], v[142:145], v[98:113]
	s_waitcnt lgkmcnt(1)
	v_mfma_f32_32x32x16_bf16 v[82:97], v[134:137], v[138:141], v[82:97]
	s_waitcnt lgkmcnt(0)
	v_mfma_f32_32x32x16_bf16 v[98:113], v[184:187], v[138:141], v[98:113]
.Lat_noqk_10:
	s_add_i32 s5, s5, 1
	s_mov_b32 s12, s13
	s_add_i32 s13, s13, 9216
	s_cmp_eq_u32 s13, 27648
	s_cselect_b32 s13, 0, s13
	s_add_i32 s16, s81, 1
	s_cmp_gt_i32 s5, s16
	s_cbranch_scc1 .Lat_novpre_11
	s_add_i32 s8, s5, -1
	s_and_b32 s8, s8, 3
	s_mul_i32 s11, s8, 20480
	v_add_u32_e32 v215, s11, v201
	ds_read_b64_tr_b16 v[224:225], v215 offset:27648
	ds_read_b64_tr_b16 v[226:227], v215 offset:30208
	ds_read_b64_tr_b16 v[228:229], v215 offset:27712
	ds_read_b64_tr_b16 v[230:231], v215 offset:30272
	ds_read_b64_tr_b16 v[232:233], v215 offset:27776
	ds_read_b64_tr_b16 v[234:235], v215 offset:30336
	ds_read_b64_tr_b16 v[236:237], v215 offset:27840
	ds_read_b64_tr_b16 v[238:239], v215 offset:30400
	s_waitcnt lgkmcnt(8)
	s_barrier
	s_branch .Lat_joined_12

.Lat_joined_12:
	s_cmp_lt_u32 s5, s6
	s_cbranch_scc1 .Lat_loop
	s_add_i32 s16, s81, 1
	s_cmp_gt_i32 s5, s16
	s_cbranch_scc1 .Lat_nolast_13
	s_add_i32 s8, s5, -1
	s_and_b32 s8, s8, 3
	s_mul_i32 s11, s8, 20480
	v_add_u32_e32 v215, s11, v201
	ds_read_b64_tr_b16 v[240:241], v215 offset:32768
	ds_read_b64_tr_b16 v[242:243], v215 offset:35328
	ds_read_b64_tr_b16 v[130:131], v215 offset:32832
	ds_read_b64_tr_b16 v[132:133], v215 offset:35392
	ds_read_b64_tr_b16 v[134:135], v215 offset:32896
	ds_read_b64_tr_b16 v[136:137], v215 offset:35456
	ds_read_b64_tr_b16 v[184:185], v215 offset:32960
	ds_read_b64_tr_b16 v[186:187], v215 offset:35520
	s_waitcnt lgkmcnt(14)
	v_mfma_f32_32x32x16_bf16 v[0:15], v[224:227], v[114:117], v[0:15]
	s_waitcnt lgkmcnt(12)
	v_mfma_f32_32x32x16_bf16 v[16:31], v[228:231], v[114:117], v[16:31]
	s_waitcnt lgkmcnt(10)
	v_mfma_f32_32x32x16_bf16 v[32:47], v[232:235], v[114:117], v[32:47]
	s_waitcnt lgkmcnt(8)
	v_mfma_f32_32x32x16_bf16 v[48:63], v[236:239], v[114:117], v[48:63]
	ds_read_b64_tr_b16 v[224:225], v215 offset:37888
	ds_read_b64_tr_b16 v[226:227], v215 offset:40448
	ds_read_b64_tr_b16 v[228:229], v215 offset:37952
	ds_read_b64_tr_b16 v[230:231], v215 offset:40512
	ds_read_b64_tr_b16 v[232:233], v215 offset:38016
	ds_read_b64_tr_b16 v[234:235], v215 offset:40576
	ds_read_b64_tr_b16 v[236:237], v215 offset:38080
	ds_read_b64_tr_b16 v[238:239], v215 offset:40640
	s_waitcnt lgkmcnt(14)
	v_mfma_f32_32x32x16_bf16 v[0:15], v[240:243], v[118:121], v[0:15]
	s_waitcnt lgkmcnt(12)
	v_mfma_f32_32x32x16_bf16 v[16:31], v[130:133], v[118:121], v[16:31]
	s_waitcnt lgkmcnt(10)
	v_mfma_f32_32x32x16_bf16 v[32:47], v[134:137], v[118:121], v[32:47]
	s_waitcnt lgkmcnt(8)
	v_mfma_f32_32x32x16_bf16 v[48:63], v[184:187], v[118:121], v[48:63]
	ds_read_b64_tr_b16 v[240:241], v215 offset:43008
	ds_read_b64_tr_b16 v[242:243], v215 offset:45568
	ds_read_b64_tr_b16 v[130:131], v215 offset:43072
	ds_read_b64_tr_b16 v[132:133], v215 offset:45632
	ds_read_b64_tr_b16 v[134:135], v215 offset:43136
	ds_read_b64_tr_b16 v[136:137], v215 offset:45696
	ds_read_b64_tr_b16 v[184:185], v215 offset:43200
	ds_read_b64_tr_b16 v[186:187], v215 offset:45760
	s_waitcnt lgkmcnt(14)
	v_mfma_f32_32x32x16_bf16 v[0:15], v[224:227], v[122:125], v[0:15]
	s_waitcnt lgkmcnt(12)
	v_mfma_f32_32x32x16_bf16 v[16:31], v[228:231], v[122:125], v[16:31]
	s_waitcnt lgkmcnt(10)
	v_mfma_f32_32x32x16_bf16 v[32:47], v[232:235], v[122:125], v[32:47]
	s_waitcnt lgkmcnt(8)
	v_mfma_f32_32x32x16_bf16 v[48:63], v[236:239], v[122:125], v[48:63]
	s_waitcnt lgkmcnt(6)
	v_mfma_f32_32x32x16_bf16 v[0:15], v[240:243], v[126:129], v[0:15]
	s_waitcnt lgkmcnt(4)
	v_mfma_f32_32x32x16_bf16 v[16:31], v[130:133], v[126:129], v[16:31]
	s_waitcnt lgkmcnt(2)
	v_mfma_f32_32x32x16_bf16 v[32:47], v[134:137], v[126:129], v[32:47]
	s_waitcnt lgkmcnt(0)
	v_mfma_f32_32x32x16_bf16 v[48:63], v[184:187], v[126:129], v[48:63]

	.amdhsa_kernel _Z8mega_fwd4Args
		.amdhsa_group_segment_fixed_size 16384
		.amdhsa_private_segment_fixed_size 0
		.amdhsa_kernarg_size 416
		.amdhsa_user_sgpr_count 2
		.amdhsa_user_sgpr_dispatch_ptr 0
		.amdhsa_user_sgpr_queue_ptr 0
		.amdhsa_user_sgpr_kernarg_segment_ptr 1
		.amdhsa_user_sgpr_dispatch_id 0
		.amdhsa_user_sgpr_kernarg_preload_length 0
		.amdhsa_user_sgpr_kernarg_preload_offset 0
		.amdhsa_user_sgpr_private_segment_size 0
		.amdhsa_uses_dynamic_stack 0
		.amdhsa_enable_private_segment 0
		.amdhsa_system_sgpr_workgroup_id_x 1
		.amdhsa_system_sgpr_workgroup_id_y 0
		.amdhsa_system_sgpr_workgroup_id_z 0
		.amdhsa_system_sgpr_workgroup_info 0
		.amdhsa_system_vgpr_workitem_id 2
		.amdhsa_next_free_vgpr 252
		.amdhsa_next_free_sgpr 102
		.amdhsa_accum_offset 252
		.amdhsa_reserve_vcc 1
		.amdhsa_float_round_mode_32 0
		.amdhsa_float_round_mode_16_64 0
		.amdhsa_float_denorm_mode_32 3
		.amdhsa_float_denorm_mode_16_64 3
		.amdhsa_dx10_clamp 1
		.amdhsa_ieee_mode 1
		.amdhsa_fp16_overflow 0
		.amdhsa_tg_split 0
		.amdhsa_exception_fp_ieee_invalid_op 0
		.amdhsa_exception_fp_denorm_src 0
		.amdhsa_exception_fp_ieee_div_zero 0
		.amdhsa_exception_fp_ieee_overflow 0
		.amdhsa_exception_fp_ieee_underflow 0
		.amdhsa_exception_fp_ieee_inexact 0
		.amdhsa_exception_int_div_zero 0
	.end_amdhsa_kernel
